# v096 + grid barrier between layer 0 out-projection and layer 1 weight-copy phase skipped (workgroup barrier kept): the copy phase overlaps the out-projection tail
# baseline (speedup 1.0000x reference)
.LBB0_695:
	v_lshl_add_u32 v148, s6, 8, v150
	s_lshl_b32 s0, s4, 8
	v_or_b32_e32 v149, s0, v152
	v_mov_b32_e32 v181, 0
	v_lshlrev_b32_e32 v180, 11, v148
	v_lshl_add_u32 v180, v149, 1, v180
	v_lshl_add_u64 v[142:143], s[40:41], 0, v[180:181]
	v_lshlrev_b32_e32 v180, 2, v149
	v_lshl_add_u64 v[178:179], s[46:47], 0, v[180:181]
	global_load_dwordx4 v[154:157], v[178:179], off
	global_load_dwordx4 v[158:161], v[178:179], off offset:16
	global_load_dwordx4 v[162:165], v[178:179], off offset:512
	global_load_dwordx4 v[166:169], v[178:179], off offset:528
	s_add_i32 s4, s0, 0x2400
	s_ashr_i32 s0, s4, 9
	s_mul_hi_i32 s4, s0, 0x1100000
	s_mul_i32 s0, s0, 0x1100000
	s_add_u32 s58, s65, s0
	s_addc_u32 s59, s66, s4
	v_and_b32_e32 v180, 0x1ff, v149
	v_lshlrev_b32_e32 v180, 1, v180
	v_lshl_add_u32 v180, v148, 10, v180
	v_lshl_add_u64 v[144:145], s[58:59], 0, v[180:181]
	v_lshlrev_b32_e32 v180, 13, v148
	v_lshl_add_u32 v180, v149, 1, v180
	v_add_u32_e32 v180, 0x1000, v180
	v_lshl_add_u64 v[146:147], s[44:45], 0, v[180:181]
	global_load_dwordx4 v[170:173], v[142:143], off
	global_load_dwordx4 v[174:177], v[144:145], off
	s_waitcnt vmcnt(2)
	v_pk_add_f32 v[126:127], v[126:127], v[154:155]
	v_pk_add_f32 v[122:123], v[122:123], v[158:159]
	v_pk_add_f32 v[128:129], v[128:129], v[156:157]
	v_pk_add_f32 v[124:125], v[124:125], v[160:161]
	v_pk_add_f32 v[118:119], v[118:119], v[162:163]
	v_pk_add_f32 v[114:115], v[114:115], v[166:167]
	v_pk_add_f32 v[120:121], v[120:121], v[164:165]
	v_pk_add_f32 v[116:117], v[116:117], v[168:169]
	v_pk_add_f32 v[110:111], v[110:111], v[154:155]
	v_pk_add_f32 v[106:107], v[106:107], v[158:159]
	v_pk_add_f32 v[112:113], v[112:113], v[156:157]
	v_pk_add_f32 v[108:109], v[108:109], v[160:161]
	v_pk_add_f32 v[102:103], v[102:103], v[162:163]
	v_pk_add_f32 v[98:99], v[98:99], v[166:167]
	v_pk_add_f32 v[104:105], v[104:105], v[164:165]
	v_pk_add_f32 v[100:101], v[100:101], v[168:169]
	v_pk_add_f32 v[94:95], v[94:95], v[154:155]
	v_pk_add_f32 v[90:91], v[90:91], v[158:159]
	v_pk_add_f32 v[96:97], v[96:97], v[156:157]
	v_pk_add_f32 v[92:93], v[92:93], v[160:161]
	v_pk_add_f32 v[86:87], v[86:87], v[162:163]
	v_pk_add_f32 v[82:83], v[82:83], v[166:167]
	v_pk_add_f32 v[88:89], v[88:89], v[164:165]
	v_pk_add_f32 v[84:85], v[84:85], v[168:169]
	v_pk_add_f32 v[78:79], v[78:79], v[154:155]
	v_pk_add_f32 v[74:75], v[74:75], v[158:159]
	v_pk_add_f32 v[80:81], v[80:81], v[156:157]
	v_pk_add_f32 v[76:77], v[76:77], v[160:161]
	v_pk_add_f32 v[70:71], v[70:71], v[162:163]
	v_pk_add_f32 v[66:67], v[66:67], v[166:167]
	v_pk_add_f32 v[72:73], v[72:73], v[164:165]
	v_pk_add_f32 v[68:69], v[68:69], v[168:169]
	v_pk_add_f32 v[62:63], v[62:63], v[154:155]
	v_pk_add_f32 v[58:59], v[58:59], v[158:159]
	v_pk_add_f32 v[64:65], v[64:65], v[156:157]
	v_pk_add_f32 v[60:61], v[60:61], v[160:161]
	v_pk_add_f32 v[54:55], v[54:55], v[162:163]
	v_pk_add_f32 v[50:51], v[50:51], v[166:167]
	v_pk_add_f32 v[56:57], v[56:57], v[164:165]
	v_pk_add_f32 v[52:53], v[52:53], v[168:169]
	v_pk_add_f32 v[46:47], v[46:47], v[154:155]
	v_pk_add_f32 v[42:43], v[42:43], v[158:159]
	v_pk_add_f32 v[48:49], v[48:49], v[156:157]
	v_pk_add_f32 v[44:45], v[44:45], v[160:161]
	v_pk_add_f32 v[38:39], v[38:39], v[162:163]
	v_pk_add_f32 v[34:35], v[34:35], v[166:167]
	v_pk_add_f32 v[40:41], v[40:41], v[164:165]
	v_pk_add_f32 v[36:37], v[36:37], v[168:169]
	v_pk_add_f32 v[30:31], v[30:31], v[154:155]
	v_pk_add_f32 v[26:27], v[26:27], v[158:159]
	v_pk_add_f32 v[32:33], v[32:33], v[156:157]
	v_pk_add_f32 v[28:29], v[28:29], v[160:161]
	v_pk_add_f32 v[22:23], v[22:23], v[162:163]
	v_pk_add_f32 v[18:19], v[18:19], v[166:167]
	v_pk_add_f32 v[24:25], v[24:25], v[164:165]
	v_pk_add_f32 v[20:21], v[20:21], v[168:169]
	v_pk_add_f32 v[14:15], v[14:15], v[154:155]
	v_pk_add_f32 v[10:11], v[10:11], v[158:159]
	v_pk_add_f32 v[16:17], v[16:17], v[156:157]
	v_pk_add_f32 v[12:13], v[12:13], v[160:161]
	v_pk_add_f32 v[6:7], v[6:7], v[162:163]
	v_pk_add_f32 v[2:3], v[2:3], v[166:167]
	v_pk_add_f32 v[8:9], v[8:9], v[164:165]
	v_pk_add_f32 v[4:5], v[4:5], v[168:169]
	global_load_dwordx4 v[154:157], v[142:143], off offset:256
	global_load_dwordx4 v[158:161], v[144:145], off offset:256
	s_mov_b64 s[58:59], 0x8000
	v_lshl_add_u64 v[142:143], v[142:143], 0, s[58:59]
	s_mov_b64 s[58:59], 0x4000
	v_lshl_add_u64 v[144:145], v[144:145], 0, s[58:59]
	global_load_dwordx4 v[162:165], v[142:143], off
	global_load_dwordx4 v[166:169], v[144:145], off
	s_waitcnt vmcnt(4)
	v_lshlrev_b32_e32 v178, 16, v170
	v_and_b32_e32 v170, 0xffff0000, v170
	v_lshlrev_b32_e32 v179, 16, v174
	v_and_b32_e32 v174, 0xffff0000, v174
	v_mul_f32_e32 v126, 0xbfb8aa3b, v126
	v_mul_f32_e32 v127, 0xbfb8aa3b, v127
	v_mul_f32_e32 v180, 0xbfb8aa3b, v179
	v_mul_f32_e32 v181, 0xbfb8aa3b, v174
	v_exp_f32_e32 v126, v126
	v_exp_f32_e32 v127, v127
	v_exp_f32_e32 v180, v180
	v_exp_f32_e32 v181, v181
	v_add_f32_e32 v126, 1.0, v126
	v_add_f32_e32 v127, 1.0, v127
	v_add_f32_e32 v180, 1.0, v180
	v_add_f32_e32 v181, 1.0, v181
	v_rcp_f32_e32 v126, v126
	v_rcp_f32_e32 v127, v127
	v_rcp_f32_e32 v180, v180
	v_rcp_f32_e32 v181, v181
	v_mul_f32_e32 v126, v126, v178
	v_mul_f32_e32 v127, v127, v170
	v_mul_f32_e32 v180, v180, v179
	v_mul_f32_e32 v181, v181, v174
	v_mul_f32_e32 v126, v126, v180
	v_mul_f32_e32 v127, v127, v181
	v_lshlrev_b32_e32 v178, 16, v171
	v_and_b32_e32 v171, 0xffff0000, v171
	v_lshlrev_b32_e32 v179, 16, v175
	v_and_b32_e32 v175, 0xffff0000, v175
	v_mul_f32_e32 v128, 0xbfb8aa3b, v128
	v_mul_f32_e32 v129, 0xbfb8aa3b, v129
	v_mul_f32_e32 v180, 0xbfb8aa3b, v179
	v_mul_f32_e32 v181, 0xbfb8aa3b, v175
	v_exp_f32_e32 v128, v128
	v_exp_f32_e32 v129, v129
	v_exp_f32_e32 v180, v180
	v_exp_f32_e32 v181, v181
	v_add_f32_e32 v128, 1.0, v128
	v_add_f32_e32 v129, 1.0, v129
	v_add_f32_e32 v180, 1.0, v180
	v_add_f32_e32 v181, 1.0, v181
	v_rcp_f32_e32 v128, v128
	v_rcp_f32_e32 v129, v129
	v_rcp_f32_e32 v180, v180
	v_rcp_f32_e32 v181, v181
	v_mul_f32_e32 v128, v128, v178
	v_mul_f32_e32 v129, v129, v171
	v_mul_f32_e32 v180, v180, v179
	v_mul_f32_e32 v181, v181, v175
	v_mul_f32_e32 v128, v128, v180
	v_mul_f32_e32 v129, v129, v181
	v_lshlrev_b32_e32 v178, 16, v172
	v_and_b32_e32 v172, 0xffff0000, v172
	v_lshlrev_b32_e32 v179, 16, v176
	v_and_b32_e32 v176, 0xffff0000, v176
	v_mul_f32_e32 v122, 0xbfb8aa3b, v122
	v_mul_f32_e32 v123, 0xbfb8aa3b, v123
	v_mul_f32_e32 v180, 0xbfb8aa3b, v179
	v_mul_f32_e32 v181, 0xbfb8aa3b, v176
	v_exp_f32_e32 v122, v122
	v_exp_f32_e32 v123, v123
	v_exp_f32_e32 v180, v180
	v_exp_f32_e32 v181, v181
	v_add_f32_e32 v122, 1.0, v122
	v_add_f32_e32 v123, 1.0, v123
	v_add_f32_e32 v180, 1.0, v180
	v_add_f32_e32 v181, 1.0, v181
	v_rcp_f32_e32 v122, v122
	v_rcp_f32_e32 v123, v123
	v_rcp_f32_e32 v180, v180
	v_rcp_f32_e32 v181, v181
	v_mul_f32_e32 v122, v122, v178
	v_mul_f32_e32 v123, v123, v172
	v_mul_f32_e32 v180, v180, v179
	v_mul_f32_e32 v181, v181, v176
	v_mul_f32_e32 v122, v122, v180
	v_mul_f32_e32 v123, v123, v181
	v_lshlrev_b32_e32 v178, 16, v173
	v_and_b32_e32 v173, 0xffff0000, v173
	v_lshlrev_b32_e32 v179, 16, v177
	v_and_b32_e32 v177, 0xffff0000, v177
	v_mul_f32_e32 v124, 0xbfb8aa3b, v124
	v_mul_f32_e32 v125, 0xbfb8aa3b, v125
	v_mul_f32_e32 v180, 0xbfb8aa3b, v179
	v_mul_f32_e32 v181, 0xbfb8aa3b, v177
	v_exp_f32_e32 v124, v124
	v_exp_f32_e32 v125, v125
	v_exp_f32_e32 v180, v180
	v_exp_f32_e32 v181, v181
	v_add_f32_e32 v124, 1.0, v124
	v_add_f32_e32 v125, 1.0, v125
	v_add_f32_e32 v180, 1.0, v180
	v_add_f32_e32 v181, 1.0, v181
	v_rcp_f32_e32 v124, v124
	v_rcp_f32_e32 v125, v125
	v_rcp_f32_e32 v180, v180
	v_rcp_f32_e32 v181, v181
	v_mul_f32_e32 v124, v124, v178
	v_mul_f32_e32 v125, v125, v173
	v_mul_f32_e32 v180, v180, v179
	v_mul_f32_e32 v181, v181, v177
	v_mul_f32_e32 v124, v124, v180
	v_mul_f32_e32 v125, v125, v181
	v_cvt_pk_bf16_f32 v126, v126, v127
	v_cvt_pk_bf16_f32 v127, v128, v129
	v_cvt_pk_bf16_f32 v128, v122, v123
	v_cvt_pk_bf16_f32 v129, v124, v125
	global_store_dwordx4 v[146:147], v[126:129], off
	global_load_dwordx4 v[170:173], v[142:143], off offset:256
	global_load_dwordx4 v[174:177], v[144:145], off offset:256
	s_waitcnt vmcnt(5)
	v_lshlrev_b32_e32 v178, 16, v154
	v_and_b32_e32 v154, 0xffff0000, v154
	v_lshlrev_b32_e32 v179, 16, v158
	v_and_b32_e32 v158, 0xffff0000, v158
	v_mul_f32_e32 v118, 0xbfb8aa3b, v118
	v_mul_f32_e32 v119, 0xbfb8aa3b, v119
	v_mul_f32_e32 v180, 0xbfb8aa3b, v179
	v_mul_f32_e32 v181, 0xbfb8aa3b, v158
	v_exp_f32_e32 v118, v118
	v_exp_f32_e32 v119, v119
	v_exp_f32_e32 v180, v180
	v_exp_f32_e32 v181, v181
	v_add_f32_e32 v118, 1.0, v118
	v_add_f32_e32 v119, 1.0, v119
	v_add_f32_e32 v180, 1.0, v180
	v_add_f32_e32 v181, 1.0, v181
	v_rcp_f32_e32 v118, v118
	v_rcp_f32_e32 v119, v119
	v_rcp_f32_e32 v180, v180
	v_rcp_f32_e32 v181, v181
	v_mul_f32_e32 v118, v118, v178
	v_mul_f32_e32 v119, v119, v154
	v_mul_f32_e32 v180, v180, v179
	v_mul_f32_e32 v181, v181, v158
	v_mul_f32_e32 v118, v118, v180
	v_mul_f32_e32 v119, v119, v181
	v_lshlrev_b32_e32 v178, 16, v155
	v_and_b32_e32 v155, 0xffff0000, v155
	v_lshlrev_b32_e32 v179, 16, v159
	v_and_b32_e32 v159, 0xffff0000, v159
	v_mul_f32_e32 v120, 0xbfb8aa3b, v120
	v_mul_f32_e32 v121, 0xbfb8aa3b, v121
	v_mul_f32_e32 v180, 0xbfb8aa3b, v179
	v_mul_f32_e32 v181, 0xbfb8aa3b, v159
	v_exp_f32_e32 v120, v120
	v_exp_f32_e32 v121, v121
	v_exp_f32_e32 v180, v180
	v_exp_f32_e32 v181, v181
	v_add_f32_e32 v120, 1.0, v120
	v_add_f32_e32 v121, 1.0, v121
	v_add_f32_e32 v180, 1.0, v180
	v_add_f32_e32 v181, 1.0, v181
	v_rcp_f32_e32 v120, v120
	v_rcp_f32_e32 v121, v121
	v_rcp_f32_e32 v180, v180
	v_rcp_f32_e32 v181, v181
	v_mul_f32_e32 v120, v120, v178
	v_mul_f32_e32 v121, v121, v155
	v_mul_f32_e32 v180, v180, v179
	v_mul_f32_e32 v181, v181, v159
	v_mul_f32_e32 v120, v120, v180
	v_mul_f32_e32 v121, v121, v181
	v_lshlrev_b32_e32 v178, 16, v156
	v_and_b32_e32 v156, 0xffff0000, v156
	v_lshlrev_b32_e32 v179, 16, v160
	v_and_b32_e32 v160, 0xffff0000, v160
	v_mul_f32_e32 v114, 0xbfb8aa3b, v114
	v_mul_f32_e32 v115, 0xbfb8aa3b, v115
	v_mul_f32_e32 v180, 0xbfb8aa3b, v179
	v_mul_f32_e32 v181, 0xbfb8aa3b, v160
	v_exp_f32_e32 v114, v114
	v_exp_f32_e32 v115, v115
	v_exp_f32_e32 v180, v180
	v_exp_f32_e32 v181, v181
	v_add_f32_e32 v114, 1.0, v114
	v_add_f32_e32 v115, 1.0, v115
	v_add_f32_e32 v180, 1.0, v180
	v_add_f32_e32 v181, 1.0, v181
	v_rcp_f32_e32 v114, v114
	v_rcp_f32_e32 v115, v115
	v_rcp_f32_e32 v180, v180
	v_rcp_f32_e32 v181, v181
	v_mul_f32_e32 v114, v114, v178
	v_mul_f32_e32 v115, v115, v156
	v_mul_f32_e32 v180, v180, v179
	v_mul_f32_e32 v181, v181, v160
	v_mul_f32_e32 v114, v114, v180
	v_mul_f32_e32 v115, v115, v181
	v_lshlrev_b32_e32 v178, 16, v157
	v_and_b32_e32 v157, 0xffff0000, v157
	v_lshlrev_b32_e32 v179, 16, v161
	v_and_b32_e32 v161, 0xffff0000, v161
	v_mul_f32_e32 v116, 0xbfb8aa3b, v116
	v_mul_f32_e32 v117, 0xbfb8aa3b, v117
	v_mul_f32_e32 v180, 0xbfb8aa3b, v179
	v_mul_f32_e32 v181, 0xbfb8aa3b, v161
	v_exp_f32_e32 v116, v116
	v_exp_f32_e32 v117, v117
	v_exp_f32_e32 v180, v180
	v_exp_f32_e32 v181, v181
	v_add_f32_e32 v116, 1.0, v116
	v_add_f32_e32 v117, 1.0, v117
	v_add_f32_e32 v180, 1.0, v180
	v_add_f32_e32 v181, 1.0, v181
	v_rcp_f32_e32 v116, v116
	v_rcp_f32_e32 v117, v117
	v_rcp_f32_e32 v180, v180
	v_rcp_f32_e32 v181, v181
	v_mul_f32_e32 v116, v116, v178
	v_mul_f32_e32 v117, v117, v157
	v_mul_f32_e32 v180, v180, v179
	v_mul_f32_e32 v181, v181, v161
	v_mul_f32_e32 v116, v116, v180
	v_mul_f32_e32 v117, v117, v181
	v_cvt_pk_bf16_f32 v118, v118, v119
	v_cvt_pk_bf16_f32 v119, v120, v121
	v_cvt_pk_bf16_f32 v120, v114, v115
	v_cvt_pk_bf16_f32 v121, v116, v117
	global_store_dwordx4 v[146:147], v[118:121], off offset:256
	s_mov_b64 s[58:59], 0x20000
	v_lshl_add_u64 v[146:147], v[146:147], 0, s[58:59]
	s_mov_b64 s[58:59], 0x8000
	v_lshl_add_u64 v[142:143], v[142:143], 0, s[58:59]
	s_mov_b64 s[58:59], 0x4000
	v_lshl_add_u64 v[144:145], v[144:145], 0, s[58:59]
	global_load_dwordx4 v[154:157], v[142:143], off
	global_load_dwordx4 v[158:161], v[144:145], off
	s_waitcnt vmcnt(6)
	v_lshlrev_b32_e32 v178, 16, v162
	v_and_b32_e32 v162, 0xffff0000, v162
	v_lshlrev_b32_e32 v179, 16, v166
	v_and_b32_e32 v166, 0xffff0000, v166
	v_mul_f32_e32 v110, 0xbfb8aa3b, v110
	v_mul_f32_e32 v111, 0xbfb8aa3b, v111
	v_mul_f32_e32 v180, 0xbfb8aa3b, v179
	v_mul_f32_e32 v181, 0xbfb8aa3b, v166
	v_exp_f32_e32 v110, v110
	v_exp_f32_e32 v111, v111
	v_exp_f32_e32 v180, v180
	v_exp_f32_e32 v181, v181
	v_add_f32_e32 v110, 1.0, v110
	v_add_f32_e32 v111, 1.0, v111
	v_add_f32_e32 v180, 1.0, v180
	v_add_f32_e32 v181, 1.0, v181
	v_rcp_f32_e32 v110, v110
	v_rcp_f32_e32 v111, v111
	v_rcp_f32_e32 v180, v180
	v_rcp_f32_e32 v181, v181
	v_mul_f32_e32 v110, v110, v178
	v_mul_f32_e32 v111, v111, v162
	v_mul_f32_e32 v180, v180, v179
	v_mul_f32_e32 v181, v181, v166
	v_mul_f32_e32 v110, v110, v180
	v_mul_f32_e32 v111, v111, v181
	v_lshlrev_b32_e32 v178, 16, v163
	v_and_b32_e32 v163, 0xffff0000, v163
	v_lshlrev_b32_e32 v179, 16, v167
	v_and_b32_e32 v167, 0xffff0000, v167
	v_mul_f32_e32 v112, 0xbfb8aa3b, v112
	v_mul_f32_e32 v113, 0xbfb8aa3b, v113
	v_mul_f32_e32 v180, 0xbfb8aa3b, v179
	v_mul_f32_e32 v181, 0xbfb8aa3b, v167
	v_exp_f32_e32 v112, v112
	v_exp_f32_e32 v113, v113
	v_exp_f32_e32 v180, v180
	v_exp_f32_e32 v181, v181
	v_add_f32_e32 v112, 1.0, v112
	v_add_f32_e32 v113, 1.0, v113
	v_add_f32_e32 v180, 1.0, v180
	v_add_f32_e32 v181, 1.0, v181
	v_rcp_f32_e32 v112, v112
	v_rcp_f32_e32 v113, v113
	v_rcp_f32_e32 v180, v180
	v_rcp_f32_e32 v181, v181
	v_mul_f32_e32 v112, v112, v178
	v_mul_f32_e32 v113, v113, v163
	v_mul_f32_e32 v180, v180, v179
	v_mul_f32_e32 v181, v181, v167
	v_mul_f32_e32 v112, v112, v180
	v_mul_f32_e32 v113, v113, v181
	v_lshlrev_b32_e32 v178, 16, v164
	v_and_b32_e32 v164, 0xffff0000, v164
	v_lshlrev_b32_e32 v179, 16, v168
	v_and_b32_e32 v168, 0xffff0000, v168
	v_mul_f32_e32 v106, 0xbfb8aa3b, v106
	v_mul_f32_e32 v107, 0xbfb8aa3b, v107
	v_mul_f32_e32 v180, 0xbfb8aa3b, v179
	v_mul_f32_e32 v181, 0xbfb8aa3b, v168
	v_exp_f32_e32 v106, v106
	v_exp_f32_e32 v107, v107
	v_exp_f32_e32 v180, v180
	v_exp_f32_e32 v181, v181
	v_add_f32_e32 v106, 1.0, v106
	v_add_f32_e32 v107, 1.0, v107
	v_add_f32_e32 v180, 1.0, v180
	v_add_f32_e32 v181, 1.0, v181
	v_rcp_f32_e32 v106, v106
	v_rcp_f32_e32 v107, v107
	v_rcp_f32_e32 v180, v180
	v_rcp_f32_e32 v181, v181
	v_mul_f32_e32 v106, v106, v178
	v_mul_f32_e32 v107, v107, v164
	v_mul_f32_e32 v180, v180, v179
	v_mul_f32_e32 v181, v181, v168
	v_mul_f32_e32 v106, v106, v180
	v_mul_f32_e32 v107, v107, v181
	v_lshlrev_b32_e32 v178, 16, v165
	v_and_b32_e32 v165, 0xffff0000, v165
	v_lshlrev_b32_e32 v179, 16, v169
	v_and_b32_e32 v169, 0xffff0000, v169
	v_mul_f32_e32 v108, 0xbfb8aa3b, v108
	v_mul_f32_e32 v109, 0xbfb8aa3b, v109
	v_mul_f32_e32 v180, 0xbfb8aa3b, v179
	v_mul_f32_e32 v181, 0xbfb8aa3b, v169
	v_exp_f32_e32 v108, v108
	v_exp_f32_e32 v109, v109
	v_exp_f32_e32 v180, v180
	v_exp_f32_e32 v181, v181
	v_add_f32_e32 v108, 1.0, v108
	v_add_f32_e32 v109, 1.0, v109
	v_add_f32_e32 v180, 1.0, v180
	v_add_f32_e32 v181, 1.0, v181
	v_rcp_f32_e32 v108, v108
	v_rcp_f32_e32 v109, v109
	v_rcp_f32_e32 v180, v180
	v_rcp_f32_e32 v181, v181
	v_mul_f32_e32 v108, v108, v178
	v_mul_f32_e32 v109, v109, v165
	v_mul_f32_e32 v180, v180, v179
	v_mul_f32_e32 v181, v181, v169
	v_mul_f32_e32 v108, v108, v180
	v_mul_f32_e32 v109, v109, v181
	v_cvt_pk_bf16_f32 v110, v110, v111
	v_cvt_pk_bf16_f32 v111, v112, v113
	v_cvt_pk_bf16_f32 v112, v106, v107
	v_cvt_pk_bf16_f32 v113, v108, v109
	global_store_dwordx4 v[146:147], v[110:113], off
	global_load_dwordx4 v[162:165], v[142:143], off offset:256
	global_load_dwordx4 v[166:169], v[144:145], off offset:256
	s_waitcnt vmcnt(6)
	v_lshlrev_b32_e32 v178, 16, v170
	v_and_b32_e32 v170, 0xffff0000, v170
	v_lshlrev_b32_e32 v179, 16, v174
	v_and_b32_e32 v174, 0xffff0000, v174
	v_mul_f32_e32 v102, 0xbfb8aa3b, v102
	v_mul_f32_e32 v103, 0xbfb8aa3b, v103
	v_mul_f32_e32 v180, 0xbfb8aa3b, v179
	v_mul_f32_e32 v181, 0xbfb8aa3b, v174
	v_exp_f32_e32 v102, v102
	v_exp_f32_e32 v103, v103
	v_exp_f32_e32 v180, v180
	v_exp_f32_e32 v181, v181
	v_add_f32_e32 v102, 1.0, v102
	v_add_f32_e32 v103, 1.0, v103
	v_add_f32_e32 v180, 1.0, v180
	v_add_f32_e32 v181, 1.0, v181
	v_rcp_f32_e32 v102, v102
	v_rcp_f32_e32 v103, v103
	v_rcp_f32_e32 v180, v180
	v_rcp_f32_e32 v181, v181
	v_mul_f32_e32 v102, v102, v178
	v_mul_f32_e32 v103, v103, v170
	v_mul_f32_e32 v180, v180, v179
	v_mul_f32_e32 v181, v181, v174
	v_mul_f32_e32 v102, v102, v180
	v_mul_f32_e32 v103, v103, v181
	v_lshlrev_b32_e32 v178, 16, v171
	v_and_b32_e32 v171, 0xffff0000, v171
	v_lshlrev_b32_e32 v179, 16, v175
	v_and_b32_e32 v175, 0xffff0000, v175
	v_mul_f32_e32 v104, 0xbfb8aa3b, v104
	v_mul_f32_e32 v105, 0xbfb8aa3b, v105
	v_mul_f32_e32 v180, 0xbfb8aa3b, v179
	v_mul_f32_e32 v181, 0xbfb8aa3b, v175
	v_exp_f32_e32 v104, v104
	v_exp_f32_e32 v105, v105
	v_exp_f32_e32 v180, v180
	v_exp_f32_e32 v181, v181
	v_add_f32_e32 v104, 1.0, v104
	v_add_f32_e32 v105, 1.0, v105
	v_add_f32_e32 v180, 1.0, v180
	v_add_f32_e32 v181, 1.0, v181
	v_rcp_f32_e32 v104, v104
	v_rcp_f32_e32 v105, v105
	v_rcp_f32_e32 v180, v180
	v_rcp_f32_e32 v181, v181
	v_mul_f32_e32 v104, v104, v178
	v_mul_f32_e32 v105, v105, v171
	v_mul_f32_e32 v180, v180, v179
	v_mul_f32_e32 v181, v181, v175
	v_mul_f32_e32 v104, v104, v180
	v_mul_f32_e32 v105, v105, v181
	v_lshlrev_b32_e32 v178, 16, v172
	v_and_b32_e32 v172, 0xffff0000, v172
	v_lshlrev_b32_e32 v179, 16, v176
	v_and_b32_e32 v176, 0xffff0000, v176
	v_mul_f32_e32 v98, 0xbfb8aa3b, v98
	v_mul_f32_e32 v99, 0xbfb8aa3b, v99
	v_mul_f32_e32 v180, 0xbfb8aa3b, v179
	v_mul_f32_e32 v181, 0xbfb8aa3b, v176
	v_exp_f32_e32 v98, v98
	v_exp_f32_e32 v99, v99
	v_exp_f32_e32 v180, v180
	v_exp_f32_e32 v181, v181
	v_add_f32_e32 v98, 1.0, v98
	v_add_f32_e32 v99, 1.0, v99
	v_add_f32_e32 v180, 1.0, v180
	v_add_f32_e32 v181, 1.0, v181
	v_rcp_f32_e32 v98, v98
	v_rcp_f32_e32 v99, v99
	v_rcp_f32_e32 v180, v180
	v_rcp_f32_e32 v181, v181
	v_mul_f32_e32 v98, v98, v178
	v_mul_f32_e32 v99, v99, v172
	v_mul_f32_e32 v180, v180, v179
	v_mul_f32_e32 v181, v181, v176
	v_mul_f32_e32 v98, v98, v180
	v_mul_f32_e32 v99, v99, v181
	v_lshlrev_b32_e32 v178, 16, v173
	v_and_b32_e32 v173, 0xffff0000, v173
	v_lshlrev_b32_e32 v179, 16, v177
	v_and_b32_e32 v177, 0xffff0000, v177
	v_mul_f32_e32 v100, 0xbfb8aa3b, v100
	v_mul_f32_e32 v101, 0xbfb8aa3b, v101
	v_mul_f32_e32 v180, 0xbfb8aa3b, v179
	v_mul_f32_e32 v181, 0xbfb8aa3b, v177
	v_exp_f32_e32 v100, v100
	v_exp_f32_e32 v101, v101
	v_exp_f32_e32 v180, v180
	v_exp_f32_e32 v181, v181
	v_add_f32_e32 v100, 1.0, v100
	v_add_f32_e32 v101, 1.0, v101
	v_add_f32_e32 v180, 1.0, v180
	v_add_f32_e32 v181, 1.0, v181
	v_rcp_f32_e32 v100, v100
	v_rcp_f32_e32 v101, v101
	v_rcp_f32_e32 v180, v180
	v_rcp_f32_e32 v181, v181
	v_mul_f32_e32 v100, v100, v178
	v_mul_f32_e32 v101, v101, v173
	v_mul_f32_e32 v180, v180, v179
	v_mul_f32_e32 v181, v181, v177
	v_mul_f32_e32 v100, v100, v180
	v_mul_f32_e32 v101, v101, v181
	v_cvt_pk_bf16_f32 v102, v102, v103
	v_cvt_pk_bf16_f32 v103, v104, v105
	v_cvt_pk_bf16_f32 v104, v98, v99
	v_cvt_pk_bf16_f32 v105, v100, v101
	global_store_dwordx4 v[146:147], v[102:105], off offset:256
	s_mov_b64 s[58:59], 0x20000
	v_lshl_add_u64 v[146:147], v[146:147], 0, s[58:59]
	s_mov_b64 s[58:59], 0x8000
	v_lshl_add_u64 v[142:143], v[142:143], 0, s[58:59]
	s_mov_b64 s[58:59], 0x4000
	v_lshl_add_u64 v[144:145], v[144:145], 0, s[58:59]
	global_load_dwordx4 v[170:173], v[142:143], off
	global_load_dwordx4 v[174:177], v[144:145], off
	s_waitcnt vmcnt(6)
	v_lshlrev_b32_e32 v178, 16, v154
	v_and_b32_e32 v154, 0xffff0000, v154
	v_lshlrev_b32_e32 v179, 16, v158
	v_and_b32_e32 v158, 0xffff0000, v158
	v_mul_f32_e32 v94, 0xbfb8aa3b, v94
	v_mul_f32_e32 v95, 0xbfb8aa3b, v95
	v_mul_f32_e32 v180, 0xbfb8aa3b, v179
	v_mul_f32_e32 v181, 0xbfb8aa3b, v158
	v_exp_f32_e32 v94, v94
	v_exp_f32_e32 v95, v95
	v_exp_f32_e32 v180, v180
	v_exp_f32_e32 v181, v181
	v_add_f32_e32 v94, 1.0, v94
	v_add_f32_e32 v95, 1.0, v95
	v_add_f32_e32 v180, 1.0, v180
	v_add_f32_e32 v181, 1.0, v181
	v_rcp_f32_e32 v94, v94
	v_rcp_f32_e32 v95, v95
	v_rcp_f32_e32 v180, v180
	v_rcp_f32_e32 v181, v181
	v_mul_f32_e32 v94, v94, v178
	v_mul_f32_e32 v95, v95, v154
	v_mul_f32_e32 v180, v180, v179
	v_mul_f32_e32 v181, v181, v158
	v_mul_f32_e32 v94, v94, v180
	v_mul_f32_e32 v95, v95, v181
	v_lshlrev_b32_e32 v178, 16, v155
	v_and_b32_e32 v155, 0xffff0000, v155
	v_lshlrev_b32_e32 v179, 16, v159
	v_and_b32_e32 v159, 0xffff0000, v159
	v_mul_f32_e32 v96, 0xbfb8aa3b, v96
	v_mul_f32_e32 v97, 0xbfb8aa3b, v97
	v_mul_f32_e32 v180, 0xbfb8aa3b, v179
	v_mul_f32_e32 v181, 0xbfb8aa3b, v159
	v_exp_f32_e32 v96, v96
	v_exp_f32_e32 v97, v97
	v_exp_f32_e32 v180, v180
	v_exp_f32_e32 v181, v181
	v_add_f32_e32 v96, 1.0, v96
	v_add_f32_e32 v97, 1.0, v97
	v_add_f32_e32 v180, 1.0, v180
	v_add_f32_e32 v181, 1.0, v181
	v_rcp_f32_e32 v96, v96
	v_rcp_f32_e32 v97, v97
	v_rcp_f32_e32 v180, v180
	v_rcp_f32_e32 v181, v181
	v_mul_f32_e32 v96, v96, v178
	v_mul_f32_e32 v97, v97, v155
	v_mul_f32_e32 v180, v180, v179
	v_mul_f32_e32 v181, v181, v159
	v_mul_f32_e32 v96, v96, v180
	v_mul_f32_e32 v97, v97, v181
	v_lshlrev_b32_e32 v178, 16, v156
	v_and_b32_e32 v156, 0xffff0000, v156
	v_lshlrev_b32_e32 v179, 16, v160
	v_and_b32_e32 v160, 0xffff0000, v160
	v_mul_f32_e32 v90, 0xbfb8aa3b, v90
	v_mul_f32_e32 v91, 0xbfb8aa3b, v91
	v_mul_f32_e32 v180, 0xbfb8aa3b, v179
	v_mul_f32_e32 v181, 0xbfb8aa3b, v160
	v_exp_f32_e32 v90, v90
	v_exp_f32_e32 v91, v91
	v_exp_f32_e32 v180, v180
	v_exp_f32_e32 v181, v181
	v_add_f32_e32 v90, 1.0, v90
	v_add_f32_e32 v91, 1.0, v91
	v_add_f32_e32 v180, 1.0, v180
	v_add_f32_e32 v181, 1.0, v181
	v_rcp_f32_e32 v90, v90
	v_rcp_f32_e32 v91, v91
	v_rcp_f32_e32 v180, v180
	v_rcp_f32_e32 v181, v181
	v_mul_f32_e32 v90, v90, v178
	v_mul_f32_e32 v91, v91, v156
	v_mul_f32_e32 v180, v180, v179
	v_mul_f32_e32 v181, v181, v160
	v_mul_f32_e32 v90, v90, v180
	v_mul_f32_e32 v91, v91, v181
	v_lshlrev_b32_e32 v178, 16, v157
	v_and_b32_e32 v157, 0xffff0000, v157
	v_lshlrev_b32_e32 v179, 16, v161
	v_and_b32_e32 v161, 0xffff0000, v161
	v_mul_f32_e32 v92, 0xbfb8aa3b, v92
	v_mul_f32_e32 v93, 0xbfb8aa3b, v93
	v_mul_f32_e32 v180, 0xbfb8aa3b, v179
	v_mul_f32_e32 v181, 0xbfb8aa3b, v161
	v_exp_f32_e32 v92, v92
	v_exp_f32_e32 v93, v93
	v_exp_f32_e32 v180, v180
	v_exp_f32_e32 v181, v181
	v_add_f32_e32 v92, 1.0, v92
	v_add_f32_e32 v93, 1.0, v93
	v_add_f32_e32 v180, 1.0, v180
	v_add_f32_e32 v181, 1.0, v181
	v_rcp_f32_e32 v92, v92
	v_rcp_f32_e32 v93, v93
	v_rcp_f32_e32 v180, v180
	v_rcp_f32_e32 v181, v181
	v_mul_f32_e32 v92, v92, v178
	v_mul_f32_e32 v93, v93, v157
	v_mul_f32_e32 v180, v180, v179
	v_mul_f32_e32 v181, v181, v161
	v_mul_f32_e32 v92, v92, v180
	v_mul_f32_e32 v93, v93, v181
	v_cvt_pk_bf16_f32 v94, v94, v95
	v_cvt_pk_bf16_f32 v95, v96, v97
	v_cvt_pk_bf16_f32 v96, v90, v91
	v_cvt_pk_bf16_f32 v97, v92, v93
	global_store_dwordx4 v[146:147], v[94:97], off
	global_load_dwordx4 v[154:157], v[142:143], off offset:256
	global_load_dwordx4 v[158:161], v[144:145], off offset:256
	s_waitcnt vmcnt(6)
	v_lshlrev_b32_e32 v178, 16, v162
	v_and_b32_e32 v162, 0xffff0000, v162
	v_lshlrev_b32_e32 v179, 16, v166
	v_and_b32_e32 v166, 0xffff0000, v166
	v_mul_f32_e32 v86, 0xbfb8aa3b, v86
	v_mul_f32_e32 v87, 0xbfb8aa3b, v87
	v_mul_f32_e32 v180, 0xbfb8aa3b, v179
	v_mul_f32_e32 v181, 0xbfb8aa3b, v166
	v_exp_f32_e32 v86, v86
	v_exp_f32_e32 v87, v87
	v_exp_f32_e32 v180, v180
	v_exp_f32_e32 v181, v181
	v_add_f32_e32 v86, 1.0, v86
	v_add_f32_e32 v87, 1.0, v87
	v_add_f32_e32 v180, 1.0, v180
	v_add_f32_e32 v181, 1.0, v181
	v_rcp_f32_e32 v86, v86
	v_rcp_f32_e32 v87, v87
	v_rcp_f32_e32 v180, v180
	v_rcp_f32_e32 v181, v181
	v_mul_f32_e32 v86, v86, v178
	v_mul_f32_e32 v87, v87, v162
	v_mul_f32_e32 v180, v180, v179
	v_mul_f32_e32 v181, v181, v166
	v_mul_f32_e32 v86, v86, v180
	v_mul_f32_e32 v87, v87, v181
	v_lshlrev_b32_e32 v178, 16, v163
	v_and_b32_e32 v163, 0xffff0000, v163
	v_lshlrev_b32_e32 v179, 16, v167
	v_and_b32_e32 v167, 0xffff0000, v167
	v_mul_f32_e32 v88, 0xbfb8aa3b, v88
	v_mul_f32_e32 v89, 0xbfb8aa3b, v89
	v_mul_f32_e32 v180, 0xbfb8aa3b, v179
	v_mul_f32_e32 v181, 0xbfb8aa3b, v167
	v_exp_f32_e32 v88, v88
	v_exp_f32_e32 v89, v89
	v_exp_f32_e32 v180, v180
	v_exp_f32_e32 v181, v181
	v_add_f32_e32 v88, 1.0, v88
	v_add_f32_e32 v89, 1.0, v89
	v_add_f32_e32 v180, 1.0, v180
	v_add_f32_e32 v181, 1.0, v181
	v_rcp_f32_e32 v88, v88
	v_rcp_f32_e32 v89, v89
	v_rcp_f32_e32 v180, v180
	v_rcp_f32_e32 v181, v181
	v_mul_f32_e32 v88, v88, v178
	v_mul_f32_e32 v89, v89, v163
	v_mul_f32_e32 v180, v180, v179
	v_mul_f32_e32 v181, v181, v167
	v_mul_f32_e32 v88, v88, v180
	v_mul_f32_e32 v89, v89, v181
	v_lshlrev_b32_e32 v178, 16, v164
	v_and_b32_e32 v164, 0xffff0000, v164
	v_lshlrev_b32_e32 v179, 16, v168
	v_and_b32_e32 v168, 0xffff0000, v168
	v_mul_f32_e32 v82, 0xbfb8aa3b, v82
	v_mul_f32_e32 v83, 0xbfb8aa3b, v83
	v_mul_f32_e32 v180, 0xbfb8aa3b, v179
	v_mul_f32_e32 v181, 0xbfb8aa3b, v168
	v_exp_f32_e32 v82, v82
	v_exp_f32_e32 v83, v83
	v_exp_f32_e32 v180, v180
	v_exp_f32_e32 v181, v181
	v_add_f32_e32 v82, 1.0, v82
	v_add_f32_e32 v83, 1.0, v83
	v_add_f32_e32 v180, 1.0, v180
	v_add_f32_e32 v181, 1.0, v181
	v_rcp_f32_e32 v82, v82
	v_rcp_f32_e32 v83, v83
	v_rcp_f32_e32 v180, v180
	v_rcp_f32_e32 v181, v181
	v_mul_f32_e32 v82, v82, v178
	v_mul_f32_e32 v83, v83, v164
	v_mul_f32_e32 v180, v180, v179
	v_mul_f32_e32 v181, v181, v168
	v_mul_f32_e32 v82, v82, v180
	v_mul_f32_e32 v83, v83, v181
	v_lshlrev_b32_e32 v178, 16, v165
	v_and_b32_e32 v165, 0xffff0000, v165
	v_lshlrev_b32_e32 v179, 16, v169
	v_and_b32_e32 v169, 0xffff0000, v169
	v_mul_f32_e32 v84, 0xbfb8aa3b, v84
	v_mul_f32_e32 v85, 0xbfb8aa3b, v85
	v_mul_f32_e32 v180, 0xbfb8aa3b, v179
	v_mul_f32_e32 v181, 0xbfb8aa3b, v169
	v_exp_f32_e32 v84, v84
	v_exp_f32_e32 v85, v85
	v_exp_f32_e32 v180, v180
	v_exp_f32_e32 v181, v181
	v_add_f32_e32 v84, 1.0, v84
	v_add_f32_e32 v85, 1.0, v85
	v_add_f32_e32 v180, 1.0, v180
	v_add_f32_e32 v181, 1.0, v181
	v_rcp_f32_e32 v84, v84
	v_rcp_f32_e32 v85, v85
	v_rcp_f32_e32 v180, v180
	v_rcp_f32_e32 v181, v181
	v_mul_f32_e32 v84, v84, v178
	v_mul_f32_e32 v85, v85, v165
	v_mul_f32_e32 v180, v180, v179
	v_mul_f32_e32 v181, v181, v169
	v_mul_f32_e32 v84, v84, v180
	v_mul_f32_e32 v85, v85, v181
	v_cvt_pk_bf16_f32 v86, v86, v87
	v_cvt_pk_bf16_f32 v87, v88, v89
	v_cvt_pk_bf16_f32 v88, v82, v83
	v_cvt_pk_bf16_f32 v89, v84, v85
	global_store_dwordx4 v[146:147], v[86:89], off offset:256
	s_mov_b64 s[58:59], 0x20000
	v_lshl_add_u64 v[146:147], v[146:147], 0, s[58:59]
	s_mov_b64 s[58:59], 0x28000
	v_lshl_add_u64 v[142:143], v[142:143], 0, s[58:59]
	s_mov_b64 s[58:59], 0x14000
	v_lshl_add_u64 v[144:145], v[144:145], 0, s[58:59]
	global_load_dwordx4 v[162:165], v[142:143], off
	global_load_dwordx4 v[166:169], v[144:145], off
	s_waitcnt vmcnt(6)
	v_lshlrev_b32_e32 v178, 16, v170
	v_and_b32_e32 v170, 0xffff0000, v170
	v_lshlrev_b32_e32 v179, 16, v174
	v_and_b32_e32 v174, 0xffff0000, v174
	v_mul_f32_e32 v78, 0xbfb8aa3b, v78
	v_mul_f32_e32 v79, 0xbfb8aa3b, v79
	v_mul_f32_e32 v180, 0xbfb8aa3b, v179
	v_mul_f32_e32 v181, 0xbfb8aa3b, v174
	v_exp_f32_e32 v78, v78
	v_exp_f32_e32 v79, v79
	v_exp_f32_e32 v180, v180
	v_exp_f32_e32 v181, v181
	v_add_f32_e32 v78, 1.0, v78
	v_add_f32_e32 v79, 1.0, v79
	v_add_f32_e32 v180, 1.0, v180
	v_add_f32_e32 v181, 1.0, v181
	v_rcp_f32_e32 v78, v78
	v_rcp_f32_e32 v79, v79
	v_rcp_f32_e32 v180, v180
	v_rcp_f32_e32 v181, v181
	v_mul_f32_e32 v78, v78, v178
	v_mul_f32_e32 v79, v79, v170
	v_mul_f32_e32 v180, v180, v179
	v_mul_f32_e32 v181, v181, v174
	v_mul_f32_e32 v78, v78, v180
	v_mul_f32_e32 v79, v79, v181
	v_lshlrev_b32_e32 v178, 16, v171
	v_and_b32_e32 v171, 0xffff0000, v171
	v_lshlrev_b32_e32 v179, 16, v175
	v_and_b32_e32 v175, 0xffff0000, v175
	v_mul_f32_e32 v80, 0xbfb8aa3b, v80
	v_mul_f32_e32 v81, 0xbfb8aa3b, v81
	v_mul_f32_e32 v180, 0xbfb8aa3b, v179
	v_mul_f32_e32 v181, 0xbfb8aa3b, v175
	v_exp_f32_e32 v80, v80
	v_exp_f32_e32 v81, v81
	v_exp_f32_e32 v180, v180
	v_exp_f32_e32 v181, v181
	v_add_f32_e32 v80, 1.0, v80
	v_add_f32_e32 v81, 1.0, v81
	v_add_f32_e32 v180, 1.0, v180
	v_add_f32_e32 v181, 1.0, v181
	v_rcp_f32_e32 v80, v80
	v_rcp_f32_e32 v81, v81
	v_rcp_f32_e32 v180, v180
	v_rcp_f32_e32 v181, v181
	v_mul_f32_e32 v80, v80, v178
	v_mul_f32_e32 v81, v81, v171
	v_mul_f32_e32 v180, v180, v179
	v_mul_f32_e32 v181, v181, v175
	v_mul_f32_e32 v80, v80, v180
	v_mul_f32_e32 v81, v81, v181
	v_lshlrev_b32_e32 v178, 16, v172
	v_and_b32_e32 v172, 0xffff0000, v172
	v_lshlrev_b32_e32 v179, 16, v176
	v_and_b32_e32 v176, 0xffff0000, v176
	v_mul_f32_e32 v74, 0xbfb8aa3b, v74
	v_mul_f32_e32 v75, 0xbfb8aa3b, v75
	v_mul_f32_e32 v180, 0xbfb8aa3b, v179
	v_mul_f32_e32 v181, 0xbfb8aa3b, v176
	v_exp_f32_e32 v74, v74
	v_exp_f32_e32 v75, v75
	v_exp_f32_e32 v180, v180
	v_exp_f32_e32 v181, v181
	v_add_f32_e32 v74, 1.0, v74
	v_add_f32_e32 v75, 1.0, v75
	v_add_f32_e32 v180, 1.0, v180
	v_add_f32_e32 v181, 1.0, v181
	v_rcp_f32_e32 v74, v74
	v_rcp_f32_e32 v75, v75
	v_rcp_f32_e32 v180, v180
	v_rcp_f32_e32 v181, v181
	v_mul_f32_e32 v74, v74, v178
	v_mul_f32_e32 v75, v75, v172
	v_mul_f32_e32 v180, v180, v179
	v_mul_f32_e32 v181, v181, v176
	v_mul_f32_e32 v74, v74, v180
	v_mul_f32_e32 v75, v75, v181
	v_lshlrev_b32_e32 v178, 16, v173
	v_and_b32_e32 v173, 0xffff0000, v173
	v_lshlrev_b32_e32 v179, 16, v177
	v_and_b32_e32 v177, 0xffff0000, v177
	v_mul_f32_e32 v76, 0xbfb8aa3b, v76
	v_mul_f32_e32 v77, 0xbfb8aa3b, v77
	v_mul_f32_e32 v180, 0xbfb8aa3b, v179
	v_mul_f32_e32 v181, 0xbfb8aa3b, v177
	v_exp_f32_e32 v76, v76
	v_exp_f32_e32 v77, v77
	v_exp_f32_e32 v180, v180
	v_exp_f32_e32 v181, v181
	v_add_f32_e32 v76, 1.0, v76
	v_add_f32_e32 v77, 1.0, v77
	v_add_f32_e32 v180, 1.0, v180
	v_add_f32_e32 v181, 1.0, v181
	v_rcp_f32_e32 v76, v76
	v_rcp_f32_e32 v77, v77
	v_rcp_f32_e32 v180, v180
	v_rcp_f32_e32 v181, v181
	v_mul_f32_e32 v76, v76, v178
	v_mul_f32_e32 v77, v77, v173
	v_mul_f32_e32 v180, v180, v179
	v_mul_f32_e32 v181, v181, v177
	v_mul_f32_e32 v76, v76, v180
	v_mul_f32_e32 v77, v77, v181
	v_cvt_pk_bf16_f32 v78, v78, v79
	v_cvt_pk_bf16_f32 v79, v80, v81
	v_cvt_pk_bf16_f32 v80, v74, v75
	v_cvt_pk_bf16_f32 v81, v76, v77
	global_store_dwordx4 v[146:147], v[78:81], off
	global_load_dwordx4 v[170:173], v[142:143], off offset:256
	global_load_dwordx4 v[174:177], v[144:145], off offset:256
	s_waitcnt vmcnt(6)
	v_lshlrev_b32_e32 v178, 16, v154
	v_and_b32_e32 v154, 0xffff0000, v154
	v_lshlrev_b32_e32 v179, 16, v158
	v_and_b32_e32 v158, 0xffff0000, v158
	v_mul_f32_e32 v70, 0xbfb8aa3b, v70
	v_mul_f32_e32 v71, 0xbfb8aa3b, v71
	v_mul_f32_e32 v180, 0xbfb8aa3b, v179
	v_mul_f32_e32 v181, 0xbfb8aa3b, v158
	v_exp_f32_e32 v70, v70
	v_exp_f32_e32 v71, v71
	v_exp_f32_e32 v180, v180
	v_exp_f32_e32 v181, v181
	v_add_f32_e32 v70, 1.0, v70
	v_add_f32_e32 v71, 1.0, v71
	v_add_f32_e32 v180, 1.0, v180
	v_add_f32_e32 v181, 1.0, v181
	v_rcp_f32_e32 v70, v70
	v_rcp_f32_e32 v71, v71
	v_rcp_f32_e32 v180, v180
	v_rcp_f32_e32 v181, v181
	v_mul_f32_e32 v70, v70, v178
	v_mul_f32_e32 v71, v71, v154
	v_mul_f32_e32 v180, v180, v179
	v_mul_f32_e32 v181, v181, v158
	v_mul_f32_e32 v70, v70, v180
	v_mul_f32_e32 v71, v71, v181
	v_lshlrev_b32_e32 v178, 16, v155
	v_and_b32_e32 v155, 0xffff0000, v155
	v_lshlrev_b32_e32 v179, 16, v159
	v_and_b32_e32 v159, 0xffff0000, v159
	v_mul_f32_e32 v72, 0xbfb8aa3b, v72
	v_mul_f32_e32 v73, 0xbfb8aa3b, v73
	v_mul_f32_e32 v180, 0xbfb8aa3b, v179
	v_mul_f32_e32 v181, 0xbfb8aa3b, v159
	v_exp_f32_e32 v72, v72
	v_exp_f32_e32 v73, v73
	v_exp_f32_e32 v180, v180
	v_exp_f32_e32 v181, v181
	v_add_f32_e32 v72, 1.0, v72
	v_add_f32_e32 v73, 1.0, v73
	v_add_f32_e32 v180, 1.0, v180
	v_add_f32_e32 v181, 1.0, v181
	v_rcp_f32_e32 v72, v72
	v_rcp_f32_e32 v73, v73
	v_rcp_f32_e32 v180, v180
	v_rcp_f32_e32 v181, v181
	v_mul_f32_e32 v72, v72, v178
	v_mul_f32_e32 v73, v73, v155
	v_mul_f32_e32 v180, v180, v179
	v_mul_f32_e32 v181, v181, v159
	v_mul_f32_e32 v72, v72, v180
	v_mul_f32_e32 v73, v73, v181
	v_lshlrev_b32_e32 v178, 16, v156
	v_and_b32_e32 v156, 0xffff0000, v156
	v_lshlrev_b32_e32 v179, 16, v160
	v_and_b32_e32 v160, 0xffff0000, v160
	v_mul_f32_e32 v66, 0xbfb8aa3b, v66
	v_mul_f32_e32 v67, 0xbfb8aa3b, v67
	v_mul_f32_e32 v180, 0xbfb8aa3b, v179
	v_mul_f32_e32 v181, 0xbfb8aa3b, v160
	v_exp_f32_e32 v66, v66
	v_exp_f32_e32 v67, v67
	v_exp_f32_e32 v180, v180
	v_exp_f32_e32 v181, v181
	v_add_f32_e32 v66, 1.0, v66
	v_add_f32_e32 v67, 1.0, v67
	v_add_f32_e32 v180, 1.0, v180
	v_add_f32_e32 v181, 1.0, v181
	v_rcp_f32_e32 v66, v66
	v_rcp_f32_e32 v67, v67
	v_rcp_f32_e32 v180, v180
	v_rcp_f32_e32 v181, v181
	v_mul_f32_e32 v66, v66, v178
	v_mul_f32_e32 v67, v67, v156
	v_mul_f32_e32 v180, v180, v179
	v_mul_f32_e32 v181, v181, v160
	v_mul_f32_e32 v66, v66, v180
	v_mul_f32_e32 v67, v67, v181
	v_lshlrev_b32_e32 v178, 16, v157
	v_and_b32_e32 v157, 0xffff0000, v157
	v_lshlrev_b32_e32 v179, 16, v161
	v_and_b32_e32 v161, 0xffff0000, v161
	v_mul_f32_e32 v68, 0xbfb8aa3b, v68
	v_mul_f32_e32 v69, 0xbfb8aa3b, v69
	v_mul_f32_e32 v180, 0xbfb8aa3b, v179
	v_mul_f32_e32 v181, 0xbfb8aa3b, v161
	v_exp_f32_e32 v68, v68
	v_exp_f32_e32 v69, v69
	v_exp_f32_e32 v180, v180
	v_exp_f32_e32 v181, v181
	v_add_f32_e32 v68, 1.0, v68
	v_add_f32_e32 v69, 1.0, v69
	v_add_f32_e32 v180, 1.0, v180
	v_add_f32_e32 v181, 1.0, v181
	v_rcp_f32_e32 v68, v68
	v_rcp_f32_e32 v69, v69
	v_rcp_f32_e32 v180, v180
	v_rcp_f32_e32 v181, v181
	v_mul_f32_e32 v68, v68, v178
	v_mul_f32_e32 v69, v69, v157
	v_mul_f32_e32 v180, v180, v179
	v_mul_f32_e32 v181, v181, v161
	v_mul_f32_e32 v68, v68, v180
	v_mul_f32_e32 v69, v69, v181
	v_cvt_pk_bf16_f32 v70, v70, v71
	v_cvt_pk_bf16_f32 v71, v72, v73
	v_cvt_pk_bf16_f32 v72, v66, v67
	v_cvt_pk_bf16_f32 v73, v68, v69
	global_store_dwordx4 v[146:147], v[70:73], off offset:256
	s_mov_b64 s[58:59], 0xa0000
	v_lshl_add_u64 v[146:147], v[146:147], 0, s[58:59]
	s_mov_b64 s[58:59], 0x8000
	v_lshl_add_u64 v[142:143], v[142:143], 0, s[58:59]
	s_mov_b64 s[58:59], 0x4000
	v_lshl_add_u64 v[144:145], v[144:145], 0, s[58:59]
	global_load_dwordx4 v[154:157], v[142:143], off
	global_load_dwordx4 v[158:161], v[144:145], off
	s_waitcnt vmcnt(6)
	v_lshlrev_b32_e32 v178, 16, v162
	v_and_b32_e32 v162, 0xffff0000, v162
	v_lshlrev_b32_e32 v179, 16, v166
	v_and_b32_e32 v166, 0xffff0000, v166
	v_mul_f32_e32 v62, 0xbfb8aa3b, v62
	v_mul_f32_e32 v63, 0xbfb8aa3b, v63
	v_mul_f32_e32 v180, 0xbfb8aa3b, v179
	v_mul_f32_e32 v181, 0xbfb8aa3b, v166
	v_exp_f32_e32 v62, v62
	v_exp_f32_e32 v63, v63
	v_exp_f32_e32 v180, v180
	v_exp_f32_e32 v181, v181
	v_add_f32_e32 v62, 1.0, v62
	v_add_f32_e32 v63, 1.0, v63
	v_add_f32_e32 v180, 1.0, v180
	v_add_f32_e32 v181, 1.0, v181
	v_rcp_f32_e32 v62, v62
	v_rcp_f32_e32 v63, v63
	v_rcp_f32_e32 v180, v180
	v_rcp_f32_e32 v181, v181
	v_mul_f32_e32 v62, v62, v178
	v_mul_f32_e32 v63, v63, v162
	v_mul_f32_e32 v180, v180, v179
	v_mul_f32_e32 v181, v181, v166
	v_mul_f32_e32 v62, v62, v180
	v_mul_f32_e32 v63, v63, v181
	v_lshlrev_b32_e32 v178, 16, v163
	v_and_b32_e32 v163, 0xffff0000, v163
	v_lshlrev_b32_e32 v179, 16, v167
	v_and_b32_e32 v167, 0xffff0000, v167
	v_mul_f32_e32 v64, 0xbfb8aa3b, v64
	v_mul_f32_e32 v65, 0xbfb8aa3b, v65
	v_mul_f32_e32 v180, 0xbfb8aa3b, v179
	v_mul_f32_e32 v181, 0xbfb8aa3b, v167
	v_exp_f32_e32 v64, v64
	v_exp_f32_e32 v65, v65
	v_exp_f32_e32 v180, v180
	v_exp_f32_e32 v181, v181
	v_add_f32_e32 v64, 1.0, v64
	v_add_f32_e32 v65, 1.0, v65
	v_add_f32_e32 v180, 1.0, v180
	v_add_f32_e32 v181, 1.0, v181
	v_rcp_f32_e32 v64, v64
	v_rcp_f32_e32 v65, v65
	v_rcp_f32_e32 v180, v180
	v_rcp_f32_e32 v181, v181
	v_mul_f32_e32 v64, v64, v178
	v_mul_f32_e32 v65, v65, v163
	v_mul_f32_e32 v180, v180, v179
	v_mul_f32_e32 v181, v181, v167
	v_mul_f32_e32 v64, v64, v180
	v_mul_f32_e32 v65, v65, v181
	v_lshlrev_b32_e32 v178, 16, v164
	v_and_b32_e32 v164, 0xffff0000, v164
	v_lshlrev_b32_e32 v179, 16, v168
	v_and_b32_e32 v168, 0xffff0000, v168
	v_mul_f32_e32 v58, 0xbfb8aa3b, v58
	v_mul_f32_e32 v59, 0xbfb8aa3b, v59
	v_mul_f32_e32 v180, 0xbfb8aa3b, v179
	v_mul_f32_e32 v181, 0xbfb8aa3b, v168
	v_exp_f32_e32 v58, v58
	v_exp_f32_e32 v59, v59
	v_exp_f32_e32 v180, v180
	v_exp_f32_e32 v181, v181
	v_add_f32_e32 v58, 1.0, v58
	v_add_f32_e32 v59, 1.0, v59
	v_add_f32_e32 v180, 1.0, v180
	v_add_f32_e32 v181, 1.0, v181
	v_rcp_f32_e32 v58, v58
	v_rcp_f32_e32 v59, v59
	v_rcp_f32_e32 v180, v180
	v_rcp_f32_e32 v181, v181
	v_mul_f32_e32 v58, v58, v178
	v_mul_f32_e32 v59, v59, v164
	v_mul_f32_e32 v180, v180, v179
	v_mul_f32_e32 v181, v181, v168
	v_mul_f32_e32 v58, v58, v180
	v_mul_f32_e32 v59, v59, v181
	v_lshlrev_b32_e32 v178, 16, v165
	v_and_b32_e32 v165, 0xffff0000, v165
	v_lshlrev_b32_e32 v179, 16, v169
	v_and_b32_e32 v169, 0xffff0000, v169
	v_mul_f32_e32 v60, 0xbfb8aa3b, v60
	v_mul_f32_e32 v61, 0xbfb8aa3b, v61
	v_mul_f32_e32 v180, 0xbfb8aa3b, v179
	v_mul_f32_e32 v181, 0xbfb8aa3b, v169
	v_exp_f32_e32 v60, v60
	v_exp_f32_e32 v61, v61
	v_exp_f32_e32 v180, v180
	v_exp_f32_e32 v181, v181
	v_add_f32_e32 v60, 1.0, v60
	v_add_f32_e32 v61, 1.0, v61
	v_add_f32_e32 v180, 1.0, v180
	v_add_f32_e32 v181, 1.0, v181
	v_rcp_f32_e32 v60, v60
	v_rcp_f32_e32 v61, v61
	v_rcp_f32_e32 v180, v180
	v_rcp_f32_e32 v181, v181
	v_mul_f32_e32 v60, v60, v178
	v_mul_f32_e32 v61, v61, v165
	v_mul_f32_e32 v180, v180, v179
	v_mul_f32_e32 v181, v181, v169
	v_mul_f32_e32 v60, v60, v180
	v_mul_f32_e32 v61, v61, v181
	v_cvt_pk_bf16_f32 v62, v62, v63
	v_cvt_pk_bf16_f32 v63, v64, v65
	v_cvt_pk_bf16_f32 v64, v58, v59
	v_cvt_pk_bf16_f32 v65, v60, v61
	global_store_dwordx4 v[146:147], v[62:65], off
	global_load_dwordx4 v[162:165], v[142:143], off offset:256
	global_load_dwordx4 v[166:169], v[144:145], off offset:256
	s_waitcnt vmcnt(6)
	v_lshlrev_b32_e32 v178, 16, v170
	v_and_b32_e32 v170, 0xffff0000, v170
	v_lshlrev_b32_e32 v179, 16, v174
	v_and_b32_e32 v174, 0xffff0000, v174
	v_mul_f32_e32 v54, 0xbfb8aa3b, v54
	v_mul_f32_e32 v55, 0xbfb8aa3b, v55
	v_mul_f32_e32 v180, 0xbfb8aa3b, v179
	v_mul_f32_e32 v181, 0xbfb8aa3b, v174
	v_exp_f32_e32 v54, v54
	v_exp_f32_e32 v55, v55
	v_exp_f32_e32 v180, v180
	v_exp_f32_e32 v181, v181
	v_add_f32_e32 v54, 1.0, v54
	v_add_f32_e32 v55, 1.0, v55
	v_add_f32_e32 v180, 1.0, v180
	v_add_f32_e32 v181, 1.0, v181
	v_rcp_f32_e32 v54, v54
	v_rcp_f32_e32 v55, v55
	v_rcp_f32_e32 v180, v180
	v_rcp_f32_e32 v181, v181
	v_mul_f32_e32 v54, v54, v178
	v_mul_f32_e32 v55, v55, v170
	v_mul_f32_e32 v180, v180, v179
	v_mul_f32_e32 v181, v181, v174
	v_mul_f32_e32 v54, v54, v180
	v_mul_f32_e32 v55, v55, v181
	v_lshlrev_b32_e32 v178, 16, v171
	v_and_b32_e32 v171, 0xffff0000, v171
	v_lshlrev_b32_e32 v179, 16, v175
	v_and_b32_e32 v175, 0xffff0000, v175
	v_mul_f32_e32 v56, 0xbfb8aa3b, v56
	v_mul_f32_e32 v57, 0xbfb8aa3b, v57
	v_mul_f32_e32 v180, 0xbfb8aa3b, v179
	v_mul_f32_e32 v181, 0xbfb8aa3b, v175
	v_exp_f32_e32 v56, v56
	v_exp_f32_e32 v57, v57
	v_exp_f32_e32 v180, v180
	v_exp_f32_e32 v181, v181
	v_add_f32_e32 v56, 1.0, v56
	v_add_f32_e32 v57, 1.0, v57
	v_add_f32_e32 v180, 1.0, v180
	v_add_f32_e32 v181, 1.0, v181
	v_rcp_f32_e32 v56, v56
	v_rcp_f32_e32 v57, v57
	v_rcp_f32_e32 v180, v180
	v_rcp_f32_e32 v181, v181
	v_mul_f32_e32 v56, v56, v178
	v_mul_f32_e32 v57, v57, v171
	v_mul_f32_e32 v180, v180, v179
	v_mul_f32_e32 v181, v181, v175
	v_mul_f32_e32 v56, v56, v180
	v_mul_f32_e32 v57, v57, v181
	v_lshlrev_b32_e32 v178, 16, v172
	v_and_b32_e32 v172, 0xffff0000, v172
	v_lshlrev_b32_e32 v179, 16, v176
	v_and_b32_e32 v176, 0xffff0000, v176
	v_mul_f32_e32 v50, 0xbfb8aa3b, v50
	v_mul_f32_e32 v51, 0xbfb8aa3b, v51
	v_mul_f32_e32 v180, 0xbfb8aa3b, v179
	v_mul_f32_e32 v181, 0xbfb8aa3b, v176
	v_exp_f32_e32 v50, v50
	v_exp_f32_e32 v51, v51
	v_exp_f32_e32 v180, v180
	v_exp_f32_e32 v181, v181
	v_add_f32_e32 v50, 1.0, v50
	v_add_f32_e32 v51, 1.0, v51
	v_add_f32_e32 v180, 1.0, v180
	v_add_f32_e32 v181, 1.0, v181
	v_rcp_f32_e32 v50, v50
	v_rcp_f32_e32 v51, v51
	v_rcp_f32_e32 v180, v180
	v_rcp_f32_e32 v181, v181
	v_mul_f32_e32 v50, v50, v178
	v_mul_f32_e32 v51, v51, v172
	v_mul_f32_e32 v180, v180, v179
	v_mul_f32_e32 v181, v181, v176
	v_mul_f32_e32 v50, v50, v180
	v_mul_f32_e32 v51, v51, v181
	v_lshlrev_b32_e32 v178, 16, v173
	v_and_b32_e32 v173, 0xffff0000, v173
	v_lshlrev_b32_e32 v179, 16, v177
	v_and_b32_e32 v177, 0xffff0000, v177
	v_mul_f32_e32 v52, 0xbfb8aa3b, v52
	v_mul_f32_e32 v53, 0xbfb8aa3b, v53
	v_mul_f32_e32 v180, 0xbfb8aa3b, v179
	v_mul_f32_e32 v181, 0xbfb8aa3b, v177
	v_exp_f32_e32 v52, v52
	v_exp_f32_e32 v53, v53
	v_exp_f32_e32 v180, v180
	v_exp_f32_e32 v181, v181
	v_add_f32_e32 v52, 1.0, v52
	v_add_f32_e32 v53, 1.0, v53
	v_add_f32_e32 v180, 1.0, v180
	v_add_f32_e32 v181, 1.0, v181
	v_rcp_f32_e32 v52, v52
	v_rcp_f32_e32 v53, v53
	v_rcp_f32_e32 v180, v180
	v_rcp_f32_e32 v181, v181
	v_mul_f32_e32 v52, v52, v178
	v_mul_f32_e32 v53, v53, v173
	v_mul_f32_e32 v180, v180, v179
	v_mul_f32_e32 v181, v181, v177
	v_mul_f32_e32 v52, v52, v180
	v_mul_f32_e32 v53, v53, v181
	v_cvt_pk_bf16_f32 v54, v54, v55
	v_cvt_pk_bf16_f32 v55, v56, v57
	v_cvt_pk_bf16_f32 v56, v50, v51
	v_cvt_pk_bf16_f32 v57, v52, v53
	global_store_dwordx4 v[146:147], v[54:57], off offset:256
	s_mov_b64 s[58:59], 0x20000
	v_lshl_add_u64 v[146:147], v[146:147], 0, s[58:59]
	s_mov_b64 s[58:59], 0x8000
	v_lshl_add_u64 v[142:143], v[142:143], 0, s[58:59]
	s_mov_b64 s[58:59], 0x4000
	v_lshl_add_u64 v[144:145], v[144:145], 0, s[58:59]
	global_load_dwordx4 v[170:173], v[142:143], off
	global_load_dwordx4 v[174:177], v[144:145], off
	s_waitcnt vmcnt(6)
	v_lshlrev_b32_e32 v178, 16, v154
	v_and_b32_e32 v154, 0xffff0000, v154
	v_lshlrev_b32_e32 v179, 16, v158
	v_and_b32_e32 v158, 0xffff0000, v158
	v_mul_f32_e32 v46, 0xbfb8aa3b, v46
	v_mul_f32_e32 v47, 0xbfb8aa3b, v47
	v_mul_f32_e32 v180, 0xbfb8aa3b, v179
	v_mul_f32_e32 v181, 0xbfb8aa3b, v158
	v_exp_f32_e32 v46, v46
	v_exp_f32_e32 v47, v47
	v_exp_f32_e32 v180, v180
	v_exp_f32_e32 v181, v181
	v_add_f32_e32 v46, 1.0, v46
	v_add_f32_e32 v47, 1.0, v47
	v_add_f32_e32 v180, 1.0, v180
	v_add_f32_e32 v181, 1.0, v181
	v_rcp_f32_e32 v46, v46
	v_rcp_f32_e32 v47, v47
	v_rcp_f32_e32 v180, v180
	v_rcp_f32_e32 v181, v181
	v_mul_f32_e32 v46, v46, v178
	v_mul_f32_e32 v47, v47, v154
	v_mul_f32_e32 v180, v180, v179
	v_mul_f32_e32 v181, v181, v158
	v_mul_f32_e32 v46, v46, v180
	v_mul_f32_e32 v47, v47, v181
	v_lshlrev_b32_e32 v178, 16, v155
	v_and_b32_e32 v155, 0xffff0000, v155
	v_lshlrev_b32_e32 v179, 16, v159
	v_and_b32_e32 v159, 0xffff0000, v159
	v_mul_f32_e32 v48, 0xbfb8aa3b, v48
	v_mul_f32_e32 v49, 0xbfb8aa3b, v49
	v_mul_f32_e32 v180, 0xbfb8aa3b, v179
	v_mul_f32_e32 v181, 0xbfb8aa3b, v159
	v_exp_f32_e32 v48, v48
	v_exp_f32_e32 v49, v49
	v_exp_f32_e32 v180, v180
	v_exp_f32_e32 v181, v181
	v_add_f32_e32 v48, 1.0, v48
	v_add_f32_e32 v49, 1.0, v49
	v_add_f32_e32 v180, 1.0, v180
	v_add_f32_e32 v181, 1.0, v181
	v_rcp_f32_e32 v48, v48
	v_rcp_f32_e32 v49, v49
	v_rcp_f32_e32 v180, v180
	v_rcp_f32_e32 v181, v181
	v_mul_f32_e32 v48, v48, v178
	v_mul_f32_e32 v49, v49, v155
	v_mul_f32_e32 v180, v180, v179
	v_mul_f32_e32 v181, v181, v159
	v_mul_f32_e32 v48, v48, v180
	v_mul_f32_e32 v49, v49, v181
	v_lshlrev_b32_e32 v178, 16, v156
	v_and_b32_e32 v156, 0xffff0000, v156
	v_lshlrev_b32_e32 v179, 16, v160
	v_and_b32_e32 v160, 0xffff0000, v160
	v_mul_f32_e32 v42, 0xbfb8aa3b, v42
	v_mul_f32_e32 v43, 0xbfb8aa3b, v43
	v_mul_f32_e32 v180, 0xbfb8aa3b, v179
	v_mul_f32_e32 v181, 0xbfb8aa3b, v160
	v_exp_f32_e32 v42, v42
	v_exp_f32_e32 v43, v43
	v_exp_f32_e32 v180, v180
	v_exp_f32_e32 v181, v181
	v_add_f32_e32 v42, 1.0, v42
	v_add_f32_e32 v43, 1.0, v43
	v_add_f32_e32 v180, 1.0, v180
	v_add_f32_e32 v181, 1.0, v181
	v_rcp_f32_e32 v42, v42
	v_rcp_f32_e32 v43, v43
	v_rcp_f32_e32 v180, v180
	v_rcp_f32_e32 v181, v181
	v_mul_f32_e32 v42, v42, v178
	v_mul_f32_e32 v43, v43, v156
	v_mul_f32_e32 v180, v180, v179
	v_mul_f32_e32 v181, v181, v160
	v_mul_f32_e32 v42, v42, v180
	v_mul_f32_e32 v43, v43, v181
	v_lshlrev_b32_e32 v178, 16, v157
	v_and_b32_e32 v157, 0xffff0000, v157
	v_lshlrev_b32_e32 v179, 16, v161
	v_and_b32_e32 v161, 0xffff0000, v161
	v_mul_f32_e32 v44, 0xbfb8aa3b, v44
	v_mul_f32_e32 v45, 0xbfb8aa3b, v45
	v_mul_f32_e32 v180, 0xbfb8aa3b, v179
	v_mul_f32_e32 v181, 0xbfb8aa3b, v161
	v_exp_f32_e32 v44, v44
	v_exp_f32_e32 v45, v45
	v_exp_f32_e32 v180, v180
	v_exp_f32_e32 v181, v181
	v_add_f32_e32 v44, 1.0, v44
	v_add_f32_e32 v45, 1.0, v45
	v_add_f32_e32 v180, 1.0, v180
	v_add_f32_e32 v181, 1.0, v181
	v_rcp_f32_e32 v44, v44
	v_rcp_f32_e32 v45, v45
	v_rcp_f32_e32 v180, v180
	v_rcp_f32_e32 v181, v181
	v_mul_f32_e32 v44, v44, v178
	v_mul_f32_e32 v45, v45, v157
	v_mul_f32_e32 v180, v180, v179
	v_mul_f32_e32 v181, v181, v161
	v_mul_f32_e32 v44, v44, v180
	v_mul_f32_e32 v45, v45, v181
	v_cvt_pk_bf16_f32 v46, v46, v47
	v_cvt_pk_bf16_f32 v47, v48, v49
	v_cvt_pk_bf16_f32 v48, v42, v43
	v_cvt_pk_bf16_f32 v49, v44, v45
	global_store_dwordx4 v[146:147], v[46:49], off
	global_load_dwordx4 v[154:157], v[142:143], off offset:256
	global_load_dwordx4 v[158:161], v[144:145], off offset:256
	s_waitcnt vmcnt(6)
	v_lshlrev_b32_e32 v178, 16, v162
	v_and_b32_e32 v162, 0xffff0000, v162
	v_lshlrev_b32_e32 v179, 16, v166
	v_and_b32_e32 v166, 0xffff0000, v166
	v_mul_f32_e32 v38, 0xbfb8aa3b, v38
	v_mul_f32_e32 v39, 0xbfb8aa3b, v39
	v_mul_f32_e32 v180, 0xbfb8aa3b, v179
	v_mul_f32_e32 v181, 0xbfb8aa3b, v166
	v_exp_f32_e32 v38, v38
	v_exp_f32_e32 v39, v39
	v_exp_f32_e32 v180, v180
	v_exp_f32_e32 v181, v181
	v_add_f32_e32 v38, 1.0, v38
	v_add_f32_e32 v39, 1.0, v39
	v_add_f32_e32 v180, 1.0, v180
	v_add_f32_e32 v181, 1.0, v181
	v_rcp_f32_e32 v38, v38
	v_rcp_f32_e32 v39, v39
	v_rcp_f32_e32 v180, v180
	v_rcp_f32_e32 v181, v181
	v_mul_f32_e32 v38, v38, v178
	v_mul_f32_e32 v39, v39, v162
	v_mul_f32_e32 v180, v180, v179
	v_mul_f32_e32 v181, v181, v166
	v_mul_f32_e32 v38, v38, v180
	v_mul_f32_e32 v39, v39, v181
	v_lshlrev_b32_e32 v178, 16, v163
	v_and_b32_e32 v163, 0xffff0000, v163
	v_lshlrev_b32_e32 v179, 16, v167
	v_and_b32_e32 v167, 0xffff0000, v167
	v_mul_f32_e32 v40, 0xbfb8aa3b, v40
	v_mul_f32_e32 v41, 0xbfb8aa3b, v41
	v_mul_f32_e32 v180, 0xbfb8aa3b, v179
	v_mul_f32_e32 v181, 0xbfb8aa3b, v167
	v_exp_f32_e32 v40, v40
	v_exp_f32_e32 v41, v41
	v_exp_f32_e32 v180, v180
	v_exp_f32_e32 v181, v181
	v_add_f32_e32 v40, 1.0, v40
	v_add_f32_e32 v41, 1.0, v41
	v_add_f32_e32 v180, 1.0, v180
	v_add_f32_e32 v181, 1.0, v181
	v_rcp_f32_e32 v40, v40
	v_rcp_f32_e32 v41, v41
	v_rcp_f32_e32 v180, v180
	v_rcp_f32_e32 v181, v181
	v_mul_f32_e32 v40, v40, v178
	v_mul_f32_e32 v41, v41, v163
	v_mul_f32_e32 v180, v180, v179
	v_mul_f32_e32 v181, v181, v167
	v_mul_f32_e32 v40, v40, v180
	v_mul_f32_e32 v41, v41, v181
	v_lshlrev_b32_e32 v178, 16, v164
	v_and_b32_e32 v164, 0xffff0000, v164
	v_lshlrev_b32_e32 v179, 16, v168
	v_and_b32_e32 v168, 0xffff0000, v168
	v_mul_f32_e32 v34, 0xbfb8aa3b, v34
	v_mul_f32_e32 v35, 0xbfb8aa3b, v35
	v_mul_f32_e32 v180, 0xbfb8aa3b, v179
	v_mul_f32_e32 v181, 0xbfb8aa3b, v168
	v_exp_f32_e32 v34, v34
	v_exp_f32_e32 v35, v35
	v_exp_f32_e32 v180, v180
	v_exp_f32_e32 v181, v181
	v_add_f32_e32 v34, 1.0, v34
	v_add_f32_e32 v35, 1.0, v35
	v_add_f32_e32 v180, 1.0, v180
	v_add_f32_e32 v181, 1.0, v181
	v_rcp_f32_e32 v34, v34
	v_rcp_f32_e32 v35, v35
	v_rcp_f32_e32 v180, v180
	v_rcp_f32_e32 v181, v181
	v_mul_f32_e32 v34, v34, v178
	v_mul_f32_e32 v35, v35, v164
	v_mul_f32_e32 v180, v180, v179
	v_mul_f32_e32 v181, v181, v168
	v_mul_f32_e32 v34, v34, v180
	v_mul_f32_e32 v35, v35, v181
	v_lshlrev_b32_e32 v178, 16, v165
	v_and_b32_e32 v165, 0xffff0000, v165
	v_lshlrev_b32_e32 v179, 16, v169
	v_and_b32_e32 v169, 0xffff0000, v169
	v_mul_f32_e32 v36, 0xbfb8aa3b, v36
	v_mul_f32_e32 v37, 0xbfb8aa3b, v37
	v_mul_f32_e32 v180, 0xbfb8aa3b, v179
	v_mul_f32_e32 v181, 0xbfb8aa3b, v169
	v_exp_f32_e32 v36, v36
	v_exp_f32_e32 v37, v37
	v_exp_f32_e32 v180, v180
	v_exp_f32_e32 v181, v181
	v_add_f32_e32 v36, 1.0, v36
	v_add_f32_e32 v37, 1.0, v37
	v_add_f32_e32 v180, 1.0, v180
	v_add_f32_e32 v181, 1.0, v181
	v_rcp_f32_e32 v36, v36
	v_rcp_f32_e32 v37, v37
	v_rcp_f32_e32 v180, v180
	v_rcp_f32_e32 v181, v181
	v_mul_f32_e32 v36, v36, v178
	v_mul_f32_e32 v37, v37, v165
	v_mul_f32_e32 v180, v180, v179
	v_mul_f32_e32 v181, v181, v169
	v_mul_f32_e32 v36, v36, v180
	v_mul_f32_e32 v37, v37, v181
	v_cvt_pk_bf16_f32 v38, v38, v39
	v_cvt_pk_bf16_f32 v39, v40, v41
	v_cvt_pk_bf16_f32 v40, v34, v35
	v_cvt_pk_bf16_f32 v41, v36, v37
	global_store_dwordx4 v[146:147], v[38:41], off offset:256
	s_mov_b64 s[58:59], 0x20000
	v_lshl_add_u64 v[146:147], v[146:147], 0, s[58:59]
	s_mov_b64 s[58:59], 0x8000
	v_lshl_add_u64 v[142:143], v[142:143], 0, s[58:59]
	s_mov_b64 s[58:59], 0x4000
	v_lshl_add_u64 v[144:145], v[144:145], 0, s[58:59]
	global_load_dwordx4 v[162:165], v[142:143], off
	global_load_dwordx4 v[166:169], v[144:145], off
	s_waitcnt vmcnt(6)
	v_lshlrev_b32_e32 v178, 16, v170
	v_and_b32_e32 v170, 0xffff0000, v170
	v_lshlrev_b32_e32 v179, 16, v174
	v_and_b32_e32 v174, 0xffff0000, v174
	v_mul_f32_e32 v30, 0xbfb8aa3b, v30
	v_mul_f32_e32 v31, 0xbfb8aa3b, v31
	v_mul_f32_e32 v180, 0xbfb8aa3b, v179
	v_mul_f32_e32 v181, 0xbfb8aa3b, v174
	v_exp_f32_e32 v30, v30
	v_exp_f32_e32 v31, v31
	v_exp_f32_e32 v180, v180
	v_exp_f32_e32 v181, v181
	v_add_f32_e32 v30, 1.0, v30
	v_add_f32_e32 v31, 1.0, v31
	v_add_f32_e32 v180, 1.0, v180
	v_add_f32_e32 v181, 1.0, v181
	v_rcp_f32_e32 v30, v30
	v_rcp_f32_e32 v31, v31
	v_rcp_f32_e32 v180, v180
	v_rcp_f32_e32 v181, v181
	v_mul_f32_e32 v30, v30, v178
	v_mul_f32_e32 v31, v31, v170
	v_mul_f32_e32 v180, v180, v179
	v_mul_f32_e32 v181, v181, v174
	v_mul_f32_e32 v30, v30, v180
	v_mul_f32_e32 v31, v31, v181
	v_lshlrev_b32_e32 v178, 16, v171
	v_and_b32_e32 v171, 0xffff0000, v171
	v_lshlrev_b32_e32 v179, 16, v175
	v_and_b32_e32 v175, 0xffff0000, v175
	v_mul_f32_e32 v32, 0xbfb8aa3b, v32
	v_mul_f32_e32 v33, 0xbfb8aa3b, v33
	v_mul_f32_e32 v180, 0xbfb8aa3b, v179
	v_mul_f32_e32 v181, 0xbfb8aa3b, v175
	v_exp_f32_e32 v32, v32
	v_exp_f32_e32 v33, v33
	v_exp_f32_e32 v180, v180
	v_exp_f32_e32 v181, v181
	v_add_f32_e32 v32, 1.0, v32
	v_add_f32_e32 v33, 1.0, v33
	v_add_f32_e32 v180, 1.0, v180
	v_add_f32_e32 v181, 1.0, v181
	v_rcp_f32_e32 v32, v32
	v_rcp_f32_e32 v33, v33
	v_rcp_f32_e32 v180, v180
	v_rcp_f32_e32 v181, v181
	v_mul_f32_e32 v32, v32, v178
	v_mul_f32_e32 v33, v33, v171
	v_mul_f32_e32 v180, v180, v179
	v_mul_f32_e32 v181, v181, v175
	v_mul_f32_e32 v32, v32, v180
	v_mul_f32_e32 v33, v33, v181
	v_lshlrev_b32_e32 v178, 16, v172
	v_and_b32_e32 v172, 0xffff0000, v172
	v_lshlrev_b32_e32 v179, 16, v176
	v_and_b32_e32 v176, 0xffff0000, v176
	v_mul_f32_e32 v26, 0xbfb8aa3b, v26
	v_mul_f32_e32 v27, 0xbfb8aa3b, v27
	v_mul_f32_e32 v180, 0xbfb8aa3b, v179
	v_mul_f32_e32 v181, 0xbfb8aa3b, v176
	v_exp_f32_e32 v26, v26
	v_exp_f32_e32 v27, v27
	v_exp_f32_e32 v180, v180
	v_exp_f32_e32 v181, v181
	v_add_f32_e32 v26, 1.0, v26
	v_add_f32_e32 v27, 1.0, v27
	v_add_f32_e32 v180, 1.0, v180
	v_add_f32_e32 v181, 1.0, v181
	v_rcp_f32_e32 v26, v26
	v_rcp_f32_e32 v27, v27
	v_rcp_f32_e32 v180, v180
	v_rcp_f32_e32 v181, v181
	v_mul_f32_e32 v26, v26, v178
	v_mul_f32_e32 v27, v27, v172
	v_mul_f32_e32 v180, v180, v179
	v_mul_f32_e32 v181, v181, v176
	v_mul_f32_e32 v26, v26, v180
	v_mul_f32_e32 v27, v27, v181
	v_lshlrev_b32_e32 v178, 16, v173
	v_and_b32_e32 v173, 0xffff0000, v173
	v_lshlrev_b32_e32 v179, 16, v177
	v_and_b32_e32 v177, 0xffff0000, v177
	v_mul_f32_e32 v28, 0xbfb8aa3b, v28
	v_mul_f32_e32 v29, 0xbfb8aa3b, v29
	v_mul_f32_e32 v180, 0xbfb8aa3b, v179
	v_mul_f32_e32 v181, 0xbfb8aa3b, v177
	v_exp_f32_e32 v28, v28
	v_exp_f32_e32 v29, v29
	v_exp_f32_e32 v180, v180
	v_exp_f32_e32 v181, v181
	v_add_f32_e32 v28, 1.0, v28
	v_add_f32_e32 v29, 1.0, v29
	v_add_f32_e32 v180, 1.0, v180
	v_add_f32_e32 v181, 1.0, v181
	v_rcp_f32_e32 v28, v28
	v_rcp_f32_e32 v29, v29
	v_rcp_f32_e32 v180, v180
	v_rcp_f32_e32 v181, v181
	v_mul_f32_e32 v28, v28, v178
	v_mul_f32_e32 v29, v29, v173
	v_mul_f32_e32 v180, v180, v179
	v_mul_f32_e32 v181, v181, v177
	v_mul_f32_e32 v28, v28, v180
	v_mul_f32_e32 v29, v29, v181
	v_cvt_pk_bf16_f32 v30, v30, v31
	v_cvt_pk_bf16_f32 v31, v32, v33
	v_cvt_pk_bf16_f32 v32, v26, v27
	v_cvt_pk_bf16_f32 v33, v28, v29
	global_store_dwordx4 v[146:147], v[30:33], off
	global_load_dwordx4 v[170:173], v[142:143], off offset:256
	global_load_dwordx4 v[174:177], v[144:145], off offset:256
	s_waitcnt vmcnt(6)
	v_lshlrev_b32_e32 v178, 16, v154
	v_and_b32_e32 v154, 0xffff0000, v154
	v_lshlrev_b32_e32 v179, 16, v158
	v_and_b32_e32 v158, 0xffff0000, v158
	v_mul_f32_e32 v22, 0xbfb8aa3b, v22
	v_mul_f32_e32 v23, 0xbfb8aa3b, v23
	v_mul_f32_e32 v180, 0xbfb8aa3b, v179
	v_mul_f32_e32 v181, 0xbfb8aa3b, v158
	v_exp_f32_e32 v22, v22
	v_exp_f32_e32 v23, v23
	v_exp_f32_e32 v180, v180
	v_exp_f32_e32 v181, v181
	v_add_f32_e32 v22, 1.0, v22
	v_add_f32_e32 v23, 1.0, v23
	v_add_f32_e32 v180, 1.0, v180
	v_add_f32_e32 v181, 1.0, v181
	v_rcp_f32_e32 v22, v22
	v_rcp_f32_e32 v23, v23
	v_rcp_f32_e32 v180, v180
	v_rcp_f32_e32 v181, v181
	v_mul_f32_e32 v22, v22, v178
	v_mul_f32_e32 v23, v23, v154
	v_mul_f32_e32 v180, v180, v179
	v_mul_f32_e32 v181, v181, v158
	v_mul_f32_e32 v22, v22, v180
	v_mul_f32_e32 v23, v23, v181
	v_lshlrev_b32_e32 v178, 16, v155
	v_and_b32_e32 v155, 0xffff0000, v155
	v_lshlrev_b32_e32 v179, 16, v159
	v_and_b32_e32 v159, 0xffff0000, v159
	v_mul_f32_e32 v24, 0xbfb8aa3b, v24
	v_mul_f32_e32 v25, 0xbfb8aa3b, v25
	v_mul_f32_e32 v180, 0xbfb8aa3b, v179
	v_mul_f32_e32 v181, 0xbfb8aa3b, v159
	v_exp_f32_e32 v24, v24
	v_exp_f32_e32 v25, v25
	v_exp_f32_e32 v180, v180
	v_exp_f32_e32 v181, v181
	v_add_f32_e32 v24, 1.0, v24
	v_add_f32_e32 v25, 1.0, v25
	v_add_f32_e32 v180, 1.0, v180
	v_add_f32_e32 v181, 1.0, v181
	v_rcp_f32_e32 v24, v24
	v_rcp_f32_e32 v25, v25
	v_rcp_f32_e32 v180, v180
	v_rcp_f32_e32 v181, v181
	v_mul_f32_e32 v24, v24, v178
	v_mul_f32_e32 v25, v25, v155
	v_mul_f32_e32 v180, v180, v179
	v_mul_f32_e32 v181, v181, v159
	v_mul_f32_e32 v24, v24, v180
	v_mul_f32_e32 v25, v25, v181
	v_lshlrev_b32_e32 v178, 16, v156
	v_and_b32_e32 v156, 0xffff0000, v156
	v_lshlrev_b32_e32 v179, 16, v160
	v_and_b32_e32 v160, 0xffff0000, v160
	v_mul_f32_e32 v18, 0xbfb8aa3b, v18
	v_mul_f32_e32 v19, 0xbfb8aa3b, v19
	v_mul_f32_e32 v180, 0xbfb8aa3b, v179
	v_mul_f32_e32 v181, 0xbfb8aa3b, v160
	v_exp_f32_e32 v18, v18
	v_exp_f32_e32 v19, v19
	v_exp_f32_e32 v180, v180
	v_exp_f32_e32 v181, v181
	v_add_f32_e32 v18, 1.0, v18
	v_add_f32_e32 v19, 1.0, v19
	v_add_f32_e32 v180, 1.0, v180
	v_add_f32_e32 v181, 1.0, v181
	v_rcp_f32_e32 v18, v18
	v_rcp_f32_e32 v19, v19
	v_rcp_f32_e32 v180, v180
	v_rcp_f32_e32 v181, v181
	v_mul_f32_e32 v18, v18, v178
	v_mul_f32_e32 v19, v19, v156
	v_mul_f32_e32 v180, v180, v179
	v_mul_f32_e32 v181, v181, v160
	v_mul_f32_e32 v18, v18, v180
	v_mul_f32_e32 v19, v19, v181
	v_lshlrev_b32_e32 v178, 16, v157
	v_and_b32_e32 v157, 0xffff0000, v157
	v_lshlrev_b32_e32 v179, 16, v161
	v_and_b32_e32 v161, 0xffff0000, v161
	v_mul_f32_e32 v20, 0xbfb8aa3b, v20
	v_mul_f32_e32 v21, 0xbfb8aa3b, v21
	v_mul_f32_e32 v180, 0xbfb8aa3b, v179
	v_mul_f32_e32 v181, 0xbfb8aa3b, v161
	v_exp_f32_e32 v20, v20
	v_exp_f32_e32 v21, v21
	v_exp_f32_e32 v180, v180
	v_exp_f32_e32 v181, v181
	v_add_f32_e32 v20, 1.0, v20
	v_add_f32_e32 v21, 1.0, v21
	v_add_f32_e32 v180, 1.0, v180
	v_add_f32_e32 v181, 1.0, v181
	v_rcp_f32_e32 v20, v20
	v_rcp_f32_e32 v21, v21
	v_rcp_f32_e32 v180, v180
	v_rcp_f32_e32 v181, v181
	v_mul_f32_e32 v20, v20, v178
	v_mul_f32_e32 v21, v21, v157
	v_mul_f32_e32 v180, v180, v179
	v_mul_f32_e32 v181, v181, v161
	v_mul_f32_e32 v20, v20, v180
	v_mul_f32_e32 v21, v21, v181
	v_cvt_pk_bf16_f32 v22, v22, v23
	v_cvt_pk_bf16_f32 v23, v24, v25
	v_cvt_pk_bf16_f32 v24, v18, v19
	v_cvt_pk_bf16_f32 v25, v20, v21
	global_store_dwordx4 v[146:147], v[22:25], off offset:256
	s_mov_b64 s[58:59], 0x20000
	v_lshl_add_u64 v[146:147], v[146:147], 0, s[58:59]
	s_waitcnt vmcnt(4)
	v_lshlrev_b32_e32 v178, 16, v162
	v_and_b32_e32 v162, 0xffff0000, v162
	v_lshlrev_b32_e32 v179, 16, v166
	v_and_b32_e32 v166, 0xffff0000, v166
	v_mul_f32_e32 v14, 0xbfb8aa3b, v14
	v_mul_f32_e32 v15, 0xbfb8aa3b, v15
	v_mul_f32_e32 v180, 0xbfb8aa3b, v179
	v_mul_f32_e32 v181, 0xbfb8aa3b, v166
	v_exp_f32_e32 v14, v14
	v_exp_f32_e32 v15, v15
	v_exp_f32_e32 v180, v180
	v_exp_f32_e32 v181, v181
	v_add_f32_e32 v14, 1.0, v14
	v_add_f32_e32 v15, 1.0, v15
	v_add_f32_e32 v180, 1.0, v180
	v_add_f32_e32 v181, 1.0, v181
	v_rcp_f32_e32 v14, v14
	v_rcp_f32_e32 v15, v15
	v_rcp_f32_e32 v180, v180
	v_rcp_f32_e32 v181, v181
	v_mul_f32_e32 v14, v14, v178
	v_mul_f32_e32 v15, v15, v162
	v_mul_f32_e32 v180, v180, v179
	v_mul_f32_e32 v181, v181, v166
	v_mul_f32_e32 v14, v14, v180
	v_mul_f32_e32 v15, v15, v181
	v_lshlrev_b32_e32 v178, 16, v163
	v_and_b32_e32 v163, 0xffff0000, v163
	v_lshlrev_b32_e32 v179, 16, v167
	v_and_b32_e32 v167, 0xffff0000, v167
	v_mul_f32_e32 v16, 0xbfb8aa3b, v16
	v_mul_f32_e32 v17, 0xbfb8aa3b, v17
	v_mul_f32_e32 v180, 0xbfb8aa3b, v179
	v_mul_f32_e32 v181, 0xbfb8aa3b, v167
	v_exp_f32_e32 v16, v16
	v_exp_f32_e32 v17, v17
	v_exp_f32_e32 v180, v180
	v_exp_f32_e32 v181, v181
	v_add_f32_e32 v16, 1.0, v16
	v_add_f32_e32 v17, 1.0, v17
	v_add_f32_e32 v180, 1.0, v180
	v_add_f32_e32 v181, 1.0, v181
	v_rcp_f32_e32 v16, v16
	v_rcp_f32_e32 v17, v17
	v_rcp_f32_e32 v180, v180
	v_rcp_f32_e32 v181, v181
	v_mul_f32_e32 v16, v16, v178
	v_mul_f32_e32 v17, v17, v163
	v_mul_f32_e32 v180, v180, v179
	v_mul_f32_e32 v181, v181, v167
	v_mul_f32_e32 v16, v16, v180
	v_mul_f32_e32 v17, v17, v181
	v_lshlrev_b32_e32 v178, 16, v164
	v_and_b32_e32 v164, 0xffff0000, v164
	v_lshlrev_b32_e32 v179, 16, v168
	v_and_b32_e32 v168, 0xffff0000, v168
	v_mul_f32_e32 v10, 0xbfb8aa3b, v10
	v_mul_f32_e32 v11, 0xbfb8aa3b, v11
	v_mul_f32_e32 v180, 0xbfb8aa3b, v179
	v_mul_f32_e32 v181, 0xbfb8aa3b, v168
	v_exp_f32_e32 v10, v10
	v_exp_f32_e32 v11, v11
	v_exp_f32_e32 v180, v180
	v_exp_f32_e32 v181, v181
	v_add_f32_e32 v10, 1.0, v10
	v_add_f32_e32 v11, 1.0, v11
	v_add_f32_e32 v180, 1.0, v180
	v_add_f32_e32 v181, 1.0, v181
	v_rcp_f32_e32 v10, v10
	v_rcp_f32_e32 v11, v11
	v_rcp_f32_e32 v180, v180
	v_rcp_f32_e32 v181, v181
	v_mul_f32_e32 v10, v10, v178
	v_mul_f32_e32 v11, v11, v164
	v_mul_f32_e32 v180, v180, v179
	v_mul_f32_e32 v181, v181, v168
	v_mul_f32_e32 v10, v10, v180
	v_mul_f32_e32 v11, v11, v181
	v_lshlrev_b32_e32 v178, 16, v165
	v_and_b32_e32 v165, 0xffff0000, v165
	v_lshlrev_b32_e32 v179, 16, v169
	v_and_b32_e32 v169, 0xffff0000, v169
	v_mul_f32_e32 v12, 0xbfb8aa3b, v12
	v_mul_f32_e32 v13, 0xbfb8aa3b, v13
	v_mul_f32_e32 v180, 0xbfb8aa3b, v179
	v_mul_f32_e32 v181, 0xbfb8aa3b, v169
	v_exp_f32_e32 v12, v12
	v_exp_f32_e32 v13, v13
	v_exp_f32_e32 v180, v180
	v_exp_f32_e32 v181, v181
	v_add_f32_e32 v12, 1.0, v12
	v_add_f32_e32 v13, 1.0, v13
	v_add_f32_e32 v180, 1.0, v180
	v_add_f32_e32 v181, 1.0, v181
	v_rcp_f32_e32 v12, v12
	v_rcp_f32_e32 v13, v13
	v_rcp_f32_e32 v180, v180
	v_rcp_f32_e32 v181, v181
	v_mul_f32_e32 v12, v12, v178
	v_mul_f32_e32 v13, v13, v165
	v_mul_f32_e32 v180, v180, v179
	v_mul_f32_e32 v181, v181, v169
	v_mul_f32_e32 v12, v12, v180
	v_mul_f32_e32 v13, v13, v181
	v_cvt_pk_bf16_f32 v14, v14, v15
	v_cvt_pk_bf16_f32 v15, v16, v17
	v_cvt_pk_bf16_f32 v16, v10, v11
	v_cvt_pk_bf16_f32 v17, v12, v13
	global_store_dwordx4 v[146:147], v[14:17], off
	s_waitcnt vmcnt(2)
	v_lshlrev_b32_e32 v178, 16, v170
	v_and_b32_e32 v170, 0xffff0000, v170
	v_lshlrev_b32_e32 v179, 16, v174
	v_and_b32_e32 v174, 0xffff0000, v174
	v_mul_f32_e32 v6, 0xbfb8aa3b, v6
	v_mul_f32_e32 v7, 0xbfb8aa3b, v7
	v_mul_f32_e32 v180, 0xbfb8aa3b, v179
	v_mul_f32_e32 v181, 0xbfb8aa3b, v174
	v_exp_f32_e32 v6, v6
	v_exp_f32_e32 v7, v7
	v_exp_f32_e32 v180, v180
	v_exp_f32_e32 v181, v181
	v_add_f32_e32 v6, 1.0, v6
	v_add_f32_e32 v7, 1.0, v7
	v_add_f32_e32 v180, 1.0, v180
	v_add_f32_e32 v181, 1.0, v181
	v_rcp_f32_e32 v6, v6
	v_rcp_f32_e32 v7, v7
	v_rcp_f32_e32 v180, v180
	v_rcp_f32_e32 v181, v181
	v_mul_f32_e32 v6, v6, v178
	v_mul_f32_e32 v7, v7, v170
	v_mul_f32_e32 v180, v180, v179
	v_mul_f32_e32 v181, v181, v174
	v_mul_f32_e32 v6, v6, v180
	v_mul_f32_e32 v7, v7, v181
	v_lshlrev_b32_e32 v178, 16, v171
	v_and_b32_e32 v171, 0xffff0000, v171
	v_lshlrev_b32_e32 v179, 16, v175
	v_and_b32_e32 v175, 0xffff0000, v175
	v_mul_f32_e32 v8, 0xbfb8aa3b, v8
	v_mul_f32_e32 v9, 0xbfb8aa3b, v9
	v_mul_f32_e32 v180, 0xbfb8aa3b, v179
	v_mul_f32_e32 v181, 0xbfb8aa3b, v175
	v_exp_f32_e32 v8, v8
	v_exp_f32_e32 v9, v9
	v_exp_f32_e32 v180, v180
	v_exp_f32_e32 v181, v181
	v_add_f32_e32 v8, 1.0, v8
	v_add_f32_e32 v9, 1.0, v9
	v_add_f32_e32 v180, 1.0, v180
	v_add_f32_e32 v181, 1.0, v181
	v_rcp_f32_e32 v8, v8
	v_rcp_f32_e32 v9, v9
	v_rcp_f32_e32 v180, v180
	v_rcp_f32_e32 v181, v181
	v_mul_f32_e32 v8, v8, v178
	v_mul_f32_e32 v9, v9, v171
	v_mul_f32_e32 v180, v180, v179
	v_mul_f32_e32 v181, v181, v175
	v_mul_f32_e32 v8, v8, v180
	v_mul_f32_e32 v9, v9, v181
	v_lshlrev_b32_e32 v178, 16, v172
	v_and_b32_e32 v172, 0xffff0000, v172
	v_lshlrev_b32_e32 v179, 16, v176
	v_and_b32_e32 v176, 0xffff0000, v176
	v_mul_f32_e32 v2, 0xbfb8aa3b, v2
	v_mul_f32_e32 v3, 0xbfb8aa3b, v3
	v_mul_f32_e32 v180, 0xbfb8aa3b, v179
	v_mul_f32_e32 v181, 0xbfb8aa3b, v176
	v_exp_f32_e32 v2, v2
	v_exp_f32_e32 v3, v3
	v_exp_f32_e32 v180, v180
	v_exp_f32_e32 v181, v181
	v_add_f32_e32 v2, 1.0, v2
	v_add_f32_e32 v3, 1.0, v3
	v_add_f32_e32 v180, 1.0, v180
	v_add_f32_e32 v181, 1.0, v181
	v_rcp_f32_e32 v2, v2
	v_rcp_f32_e32 v3, v3
	v_rcp_f32_e32 v180, v180
	v_rcp_f32_e32 v181, v181
	v_mul_f32_e32 v2, v2, v178
	v_mul_f32_e32 v3, v3, v172
	v_mul_f32_e32 v180, v180, v179
	v_mul_f32_e32 v181, v181, v176
	v_mul_f32_e32 v2, v2, v180
	v_mul_f32_e32 v3, v3, v181
	v_lshlrev_b32_e32 v178, 16, v173
	v_and_b32_e32 v173, 0xffff0000, v173
	v_lshlrev_b32_e32 v179, 16, v177
	v_and_b32_e32 v177, 0xffff0000, v177
	v_mul_f32_e32 v4, 0xbfb8aa3b, v4
	v_mul_f32_e32 v5, 0xbfb8aa3b, v5
	v_mul_f32_e32 v180, 0xbfb8aa3b, v179
	v_mul_f32_e32 v181, 0xbfb8aa3b, v177
	v_exp_f32_e32 v4, v4
	v_exp_f32_e32 v5, v5
	v_exp_f32_e32 v180, v180
	v_exp_f32_e32 v181, v181
	v_add_f32_e32 v4, 1.0, v4
	v_add_f32_e32 v5, 1.0, v5
	v_add_f32_e32 v180, 1.0, v180
	v_add_f32_e32 v181, 1.0, v181
	v_rcp_f32_e32 v4, v4
	v_rcp_f32_e32 v5, v5
	v_rcp_f32_e32 v180, v180
	v_rcp_f32_e32 v181, v181
	v_mul_f32_e32 v4, v4, v178
	v_mul_f32_e32 v5, v5, v173
	v_mul_f32_e32 v180, v180, v179
	v_mul_f32_e32 v181, v181, v177
	v_mul_f32_e32 v4, v4, v180
	v_mul_f32_e32 v5, v5, v181
	v_cvt_pk_bf16_f32 v6, v6, v7
	v_cvt_pk_bf16_f32 v7, v8, v9
	v_cvt_pk_bf16_f32 v8, v2, v3
	v_cvt_pk_bf16_f32 v9, v4, v5
	global_store_dwordx4 v[146:147], v[6:9], off offset:256
	s_andn2_b64 vcc, exec, s[38:39]
	s_mov_b64 s[4:5], -1
	s_cbranch_vccnz .LBB0_686
	s_andn2_b64 vcc, exec, s[42:43]
	s_cbranch_vccnz .LBB0_685
	s_barrier
	s_branch .LBB0_685
	s_nop 0
	s_nop 0
	s_nop 0
	s_nop 0
	s_nop 0
	s_nop 0
	s_nop 0
	s_nop 0
	s_nop 0
	s_nop 0
	s_nop 0
	s_nop 0
	s_nop 0
	s_nop 0
	s_nop 0
	s_nop 0
	s_nop 0
	s_nop 0
	s_nop 0
	s_nop 0
	s_nop 0
	s_nop 0
	s_nop 0
	s_nop 0
	s_nop 0
	s_nop 0
	s_nop 0
	s_nop 0
	s_nop 0
	s_nop 0
	s_nop 0
	s_nop 0
	s_nop 0
	s_nop 0
	s_nop 0
	s_nop 0
	s_nop 0
	s_nop 0
	s_nop 0
	s_nop 0
	s_nop 0
	s_nop 0
	s_nop 0
	s_nop 0
	s_nop 0
	s_nop 0
	s_nop 0
	s_nop 0
	s_nop 0
	s_nop 0
	s_nop 0
	s_nop 0
	s_nop 0
	s_nop 0
	s_nop 0
	s_nop 0
	s_nop 0
	s_nop 0
.LBB0_698:
	v_readlane_b32 s60, v255, 0
	s_waitcnt vmcnt(0)
	v_readlane_b32 s61, v255, 1
	v_readlane_b32 s70, v254, 62
	v_readlane_b32 s60, v255, 6
	v_readlane_b32 s71, v254, 63
	v_readlane_b32 s62, v255, 2
	v_readlane_b32 s63, v255, 3
	v_readlane_b32 s61, v255, 7
	s_barrier
